# barrier trims + K-loop LDS-DMA loads sc0 (operand streams bypass the CU L1)
# speedup vs baseline: 1.0153x; 1.0017x over previous
.LBB0_262:
	s_add_i32 vcc_lo, s38, 2
	s_add_u32 s39, s10, 0xfff00080
	s_addc_u32 s66, s11, -1
	s_add_i32 s67, 0, 0x10000
	s_cmp_eq_u32 s35, s38
	s_cselect_b32 s87, s53, s66
	s_cselect_b32 s86, s52, s39
	s_cselect_b32 s39, s13, s49
	s_cselect_b32 s38, s15, s40
	s_add_i32 vcc_hi, 0, 0x14000
	v_add_u32_e32 v142, s67, v1
	v_add_u32_e32 v180, vcc_hi, v1
	ds_read_b128 v[130:133], v142
	ds_read_b128 v[134:137], v142 offset:1024
	ds_read_b128 v[138:141], v142 offset:2048
	ds_read_b128 v[142:145], v142 offset:3072
	ds_read_b128 v[168:171], v180
	ds_read_b128 v[172:175], v180 offset:1024
	ds_read_b128 v[176:179], v180 offset:2048
	ds_read_b128 v[180:183], v180 offset:3072
	v_lshl_add_u64 v[184:185], s[10:11], 0, v[164:165]
	s_add_i32 m0, s85, 0xc000
	ds_read_b128 v[198:201], v197
	ds_read_b128 v[202:205], v197 offset:1024
	ds_read_b128 v[206:209], v197 offset:2048
	ds_read_b128 v[210:213], v197 offset:3072
	ds_read_b128 v[214:217], v197 offset:4096
	ds_read_b128 v[218:221], v197 offset:5120
	ds_read_b128 v[222:225], v197 offset:6144
	ds_read_b128 v[226:229], v197 offset:7168
	global_load_lds_dwordx4 v[184:185], off sc0
	v_lshl_add_u64 v[184:185], s[10:11], 0, v[166:167]
	s_add_i32 m0, s85, 0xe000
	s_nop 0
	global_load_lds_dwordx4 v[184:185], off sc0
	s_waitcnt vmcnt(8)
	s_waitcnt lgkmcnt(0)
	s_setprio 1
	s_barrier
	v_mfma_f32_16x16x32_bf16 v[114:117], v[130:133], v[198:201], v[114:117]
	v_mfma_f32_16x16x32_bf16 v[118:121], v[138:141], v[198:201], v[118:121]
	v_mfma_f32_16x16x32_bf16 v[102:105], v[130:133], v[206:209], v[102:105]
	v_mfma_f32_16x16x32_bf16 v[98:101], v[138:141], v[206:209], v[98:101]
	v_mfma_f32_16x16x32_bf16 v[86:89], v[130:133], v[214:217], v[86:89]
	v_mfma_f32_16x16x32_bf16 v[82:85], v[138:141], v[214:217], v[82:85]
	v_mfma_f32_16x16x32_bf16 v[54:57], v[130:133], v[222:225], v[54:57]
	v_mfma_f32_16x16x32_bf16 v[50:53], v[138:141], v[222:225], v[50:53]
	v_mfma_f32_16x16x32_bf16 v[114:117], v[134:137], v[202:205], v[114:117]
	v_mfma_f32_16x16x32_bf16 v[118:121], v[142:145], v[202:205], v[118:121]
	v_mfma_f32_16x16x32_bf16 v[102:105], v[134:137], v[210:213], v[102:105]
	v_mfma_f32_16x16x32_bf16 v[98:101], v[142:145], v[210:213], v[98:101]
	v_mfma_f32_16x16x32_bf16 v[86:89], v[134:137], v[218:221], v[86:89]
	v_mfma_f32_16x16x32_bf16 v[82:85], v[142:145], v[218:221], v[82:85]
	v_mfma_f32_16x16x32_bf16 v[54:57], v[134:137], v[226:229], v[54:57]
	v_mfma_f32_16x16x32_bf16 v[50:53], v[142:145], v[226:229], v[50:53]
	s_setprio 0
	s_setprio 1
	v_mfma_f32_16x16x32_bf16 v[126:129], v[168:171], v[198:201], v[126:129]
	v_mfma_f32_16x16x32_bf16 v[122:125], v[176:179], v[198:201], v[122:125]
	v_mfma_f32_16x16x32_bf16 v[110:113], v[168:171], v[206:209], v[110:113]
	v_mfma_f32_16x16x32_bf16 v[106:109], v[176:179], v[206:209], v[106:109]
	v_mfma_f32_16x16x32_bf16 v[94:97], v[168:171], v[214:217], v[94:97]
	v_mfma_f32_16x16x32_bf16 v[90:93], v[176:179], v[214:217], v[90:93]
	v_mfma_f32_16x16x32_bf16 v[70:73], v[168:171], v[222:225], v[70:73]
	v_mfma_f32_16x16x32_bf16 v[66:69], v[176:179], v[222:225], v[66:69]
	v_mfma_f32_16x16x32_bf16 v[126:129], v[172:175], v[202:205], v[126:129]
	v_mfma_f32_16x16x32_bf16 v[122:125], v[180:183], v[202:205], v[122:125]
	v_mfma_f32_16x16x32_bf16 v[110:113], v[172:175], v[210:213], v[110:113]
	v_mfma_f32_16x16x32_bf16 v[106:109], v[180:183], v[210:213], v[106:109]
	v_mfma_f32_16x16x32_bf16 v[94:97], v[172:175], v[218:221], v[94:97]
	v_mfma_f32_16x16x32_bf16 v[90:93], v[180:183], v[218:221], v[90:93]
	v_mfma_f32_16x16x32_bf16 v[70:73], v[172:175], v[226:229], v[70:73]
	v_mfma_f32_16x16x32_bf16 v[66:69], v[180:183], v[226:229], v[66:69]
	s_barrier
	s_setprio 0
	s_add_i32 s66, s67, s97
	v_lshl_add_u64 v[184:185], s[38:39], 0, v[156:157]
	s_mov_b32 m0, s66
	ds_read_b128 v[198:201], v197 offset:16384
	ds_read_b128 v[202:205], v197 offset:17408
	ds_read_b128 v[206:209], v197 offset:18432
	ds_read_b128 v[210:213], v197 offset:19456
	ds_read_b128 v[214:217], v197 offset:20480
	ds_read_b128 v[218:221], v197 offset:21504
	ds_read_b128 v[222:225], v197 offset:22528
	ds_read_b128 v[226:229], v197 offset:23552
	global_load_lds_dwordx4 v[184:185], off sc0
	s_add_i32 m0, s66, 0x2000
	s_add_u32 s66, s38, 0x100000
	v_lshl_add_u64 v[230:231], s[38:39], 0, v[160:161]
	s_addc_u32 s67, s39, 0
	s_add_i32 vcc_hi, vcc_hi, s97
	global_load_lds_dwordx4 v[230:231], off sc0
	v_lshl_add_u64 v[232:233], s[66:67], 0, v[156:157]
	s_mov_b32 m0, vcc_hi
	v_lshl_add_u64 v[234:235], s[86:87], 0, v[158:159]
	global_load_lds_dwordx4 v[232:233], off sc0
	v_lshl_add_u64 v[232:233], s[66:67], 0, v[160:161]
	s_add_i32 m0, vcc_hi, 0x2000
	s_nop 0
	global_load_lds_dwordx4 v[232:233], off sc0
	v_lshl_add_u64 v[232:233], s[86:87], 0, v[154:155]
	s_mov_b32 m0, s85
	s_nop 0
	global_load_lds_dwordx4 v[232:233], off sc0
	s_mov_b32 m0, s92
	s_nop 0
	global_load_lds_dwordx4 v[234:235], off sc0
	s_waitcnt vmcnt(8)
	s_waitcnt lgkmcnt(0)
	s_setprio 1
	s_barrier
	v_mfma_f32_16x16x32_bf16 v[62:65], v[130:133], v[198:201], v[62:65]
	v_mfma_f32_16x16x32_bf16 v[58:61], v[138:141], v[198:201], v[58:61]
	v_mfma_f32_16x16x32_bf16 v[38:41], v[130:133], v[206:209], v[38:41]
	v_mfma_f32_16x16x32_bf16 v[34:37], v[138:141], v[206:209], v[34:37]
	v_mfma_f32_16x16x32_bf16 v[22:25], v[130:133], v[214:217], v[22:25]
	v_mfma_f32_16x16x32_bf16 v[18:21], v[138:141], v[214:217], v[18:21]
	v_mfma_f32_16x16x32_bf16 v[6:9], v[130:133], v[222:225], v[6:9]
	v_mfma_f32_16x16x32_bf16 v[2:5], v[138:141], v[222:225], v[2:5]
	v_mfma_f32_16x16x32_bf16 v[62:65], v[134:137], v[202:205], v[62:65]
	v_mfma_f32_16x16x32_bf16 v[58:61], v[142:145], v[202:205], v[58:61]
	v_mfma_f32_16x16x32_bf16 v[38:41], v[134:137], v[210:213], v[38:41]
	v_mfma_f32_16x16x32_bf16 v[34:37], v[142:145], v[210:213], v[34:37]
	v_mfma_f32_16x16x32_bf16 v[22:25], v[134:137], v[218:221], v[22:25]
	v_mfma_f32_16x16x32_bf16 v[18:21], v[142:145], v[218:221], v[18:21]
	v_mfma_f32_16x16x32_bf16 v[6:9], v[134:137], v[226:229], v[6:9]
	v_mfma_f32_16x16x32_bf16 v[2:5], v[142:145], v[226:229], v[2:5]
	s_setprio 0
	s_setprio 1
	v_mfma_f32_16x16x32_bf16 v[78:81], v[168:171], v[198:201], v[78:81]
	v_mfma_f32_16x16x32_bf16 v[74:77], v[176:179], v[198:201], v[74:77]
	v_mfma_f32_16x16x32_bf16 v[46:49], v[168:171], v[206:209], v[46:49]
	v_mfma_f32_16x16x32_bf16 v[42:45], v[176:179], v[206:209], v[42:45]
	v_mfma_f32_16x16x32_bf16 v[30:33], v[168:171], v[214:217], v[30:33]
	v_mfma_f32_16x16x32_bf16 v[26:29], v[176:179], v[214:217], v[26:29]
	v_mfma_f32_16x16x32_bf16 v[14:17], v[168:171], v[222:225], v[14:17]
	v_mfma_f32_16x16x32_bf16 v[10:13], v[176:179], v[222:225], v[10:13]
	v_mfma_f32_16x16x32_bf16 v[78:81], v[172:175], v[202:205], v[78:81]
	v_mfma_f32_16x16x32_bf16 v[74:77], v[180:183], v[202:205], v[74:77]
	v_mfma_f32_16x16x32_bf16 v[46:49], v[172:175], v[210:213], v[46:49]
	v_mfma_f32_16x16x32_bf16 v[42:45], v[180:183], v[210:213], v[42:45]
	v_mfma_f32_16x16x32_bf16 v[30:33], v[172:175], v[218:221], v[30:33]
	v_mfma_f32_16x16x32_bf16 v[26:29], v[180:183], v[218:221], v[26:29]
	v_mfma_f32_16x16x32_bf16 v[14:17], v[172:175], v[226:229], v[14:17]
	v_mfma_f32_16x16x32_bf16 v[10:13], v[180:183], v[226:229], v[10:13]
	s_barrier
	s_setprio 0
	s_add_i32 vcc_hi, 0, 0x18000
	s_add_i32 s56, 0, 0x1c000
	v_add_u32_e32 v142, vcc_hi, v1
	v_add_u32_e32 v180, s56, v1
	ds_read_b128 v[130:133], v142
	ds_read_b128 v[134:137], v142 offset:1024
	ds_read_b128 v[138:141], v142 offset:2048
	ds_read_b128 v[142:145], v142 offset:3072
	ds_read_b128 v[168:171], v180
	ds_read_b128 v[172:175], v180 offset:1024
	ds_read_b128 v[176:179], v180 offset:2048
	ds_read_b128 v[180:183], v180 offset:3072
	s_add_u32 s66, s86, 0x100000
	s_addc_u32 s67, s87, 0
	s_mov_b32 m0, s93
	v_lshl_add_u64 v[236:237], s[66:67], 0, v[154:155]
	ds_read_b128 v[198:201], v197 offset:32768
	ds_read_b128 v[202:205], v197 offset:33792
	ds_read_b128 v[206:209], v197 offset:34816
	ds_read_b128 v[210:213], v197 offset:35840
	ds_read_b128 v[214:217], v197 offset:36864
	ds_read_b128 v[218:221], v197 offset:37888
	ds_read_b128 v[222:225], v197 offset:38912
	ds_read_b128 v[226:229], v197 offset:39936
	global_load_lds_dwordx4 v[236:237], off sc0
	v_lshl_add_u64 v[236:237], s[66:67], 0, v[158:159]
	s_mov_b32 m0, s42
	s_nop 0
	global_load_lds_dwordx4 v[236:237], off sc0
	s_waitcnt vmcnt(8)
	s_waitcnt lgkmcnt(0)
	s_setprio 1
	s_barrier
	v_mfma_f32_16x16x32_bf16 v[114:117], v[130:133], v[198:201], v[114:117]
	v_mfma_f32_16x16x32_bf16 v[118:121], v[138:141], v[198:201], v[118:121]
	v_mfma_f32_16x16x32_bf16 v[102:105], v[130:133], v[206:209], v[102:105]
	v_mfma_f32_16x16x32_bf16 v[98:101], v[138:141], v[206:209], v[98:101]
	v_mfma_f32_16x16x32_bf16 v[86:89], v[130:133], v[214:217], v[86:89]
	v_mfma_f32_16x16x32_bf16 v[82:85], v[138:141], v[214:217], v[82:85]
	v_mfma_f32_16x16x32_bf16 v[54:57], v[130:133], v[222:225], v[54:57]
	v_mfma_f32_16x16x32_bf16 v[50:53], v[138:141], v[222:225], v[50:53]
	v_mfma_f32_16x16x32_bf16 v[114:117], v[134:137], v[202:205], v[114:117]
	v_mfma_f32_16x16x32_bf16 v[118:121], v[142:145], v[202:205], v[118:121]
	v_mfma_f32_16x16x32_bf16 v[102:105], v[134:137], v[210:213], v[102:105]
	v_mfma_f32_16x16x32_bf16 v[98:101], v[142:145], v[210:213], v[98:101]
	v_mfma_f32_16x16x32_bf16 v[86:89], v[134:137], v[218:221], v[86:89]
	v_mfma_f32_16x16x32_bf16 v[82:85], v[142:145], v[218:221], v[82:85]
	v_mfma_f32_16x16x32_bf16 v[54:57], v[134:137], v[226:229], v[54:57]
	v_mfma_f32_16x16x32_bf16 v[50:53], v[142:145], v[226:229], v[50:53]
	s_setprio 0
	s_setprio 1
	v_mfma_f32_16x16x32_bf16 v[126:129], v[168:171], v[198:201], v[126:129]
	v_mfma_f32_16x16x32_bf16 v[122:125], v[176:179], v[198:201], v[122:125]
	v_mfma_f32_16x16x32_bf16 v[110:113], v[168:171], v[206:209], v[110:113]
	v_mfma_f32_16x16x32_bf16 v[106:109], v[176:179], v[206:209], v[106:109]
	v_mfma_f32_16x16x32_bf16 v[94:97], v[168:171], v[214:217], v[94:97]
	v_mfma_f32_16x16x32_bf16 v[90:93], v[176:179], v[214:217], v[90:93]
	v_mfma_f32_16x16x32_bf16 v[70:73], v[168:171], v[222:225], v[70:73]
	v_mfma_f32_16x16x32_bf16 v[66:69], v[176:179], v[222:225], v[66:69]
	v_mfma_f32_16x16x32_bf16 v[126:129], v[172:175], v[202:205], v[126:129]
	v_mfma_f32_16x16x32_bf16 v[122:125], v[180:183], v[202:205], v[122:125]
	v_mfma_f32_16x16x32_bf16 v[110:113], v[172:175], v[210:213], v[110:113]
	v_mfma_f32_16x16x32_bf16 v[106:109], v[180:183], v[210:213], v[106:109]
	v_mfma_f32_16x16x32_bf16 v[94:97], v[172:175], v[218:221], v[94:97]
	v_mfma_f32_16x16x32_bf16 v[90:93], v[180:183], v[218:221], v[90:93]
	v_mfma_f32_16x16x32_bf16 v[70:73], v[172:175], v[226:229], v[70:73]
	v_mfma_f32_16x16x32_bf16 v[66:69], v[180:183], v[226:229], v[66:69]
	s_barrier
	s_setprio 0
	s_add_i32 s57, vcc_hi, s97
	v_lshl_add_u64 v[184:185], v[184:185], 0, s[94:95]
	s_mov_b32 m0, s57
	ds_read_b128 v[198:201], v197 offset:49152
	ds_read_b128 v[202:205], v197 offset:50176
	ds_read_b128 v[206:209], v197 offset:51200
	ds_read_b128 v[210:213], v197 offset:52224
	ds_read_b128 v[214:217], v197 offset:53248
	ds_read_b128 v[218:221], v197 offset:54272
	ds_read_b128 v[222:225], v197 offset:55296
	ds_read_b128 v[226:229], v197 offset:56320
	global_load_lds_dwordx4 v[184:185], off sc0
	s_add_i32 m0, s57, 0x2000
	s_add_u32 s38, s38, 0x100080
	v_lshl_add_u64 v[184:185], v[230:231], 0, s[94:95]
	s_addc_u32 s39, s39, 0
	s_add_i32 s56, s56, s97
	global_load_lds_dwordx4 v[184:185], off sc0
	v_lshl_add_u64 v[184:185], s[38:39], 0, v[156:157]
	s_mov_b32 m0, s56
	s_nop 0
	global_load_lds_dwordx4 v[184:185], off sc0
	v_lshl_add_u64 v[184:185], s[38:39], 0, v[160:161]
	s_add_i32 m0, s56, 0x2000
	s_nop 0
	global_load_lds_dwordx4 v[184:185], off sc0
	v_lshl_add_u64 v[184:185], v[232:233], 0, s[94:95]
	s_mov_b32 m0, s43
	s_nop 0
	global_load_lds_dwordx4 v[184:185], off sc0
	v_lshl_add_u64 v[184:185], v[234:235], 0, s[94:95]
	s_mov_b32 m0, s90
	s_nop 0
	global_load_lds_dwordx4 v[184:185], off sc0
	s_waitcnt vmcnt(8)
	s_waitcnt lgkmcnt(0)
	s_setprio 1
	s_barrier
	v_mfma_f32_16x16x32_bf16 v[62:65], v[130:133], v[198:201], v[62:65]
	v_mfma_f32_16x16x32_bf16 v[58:61], v[138:141], v[198:201], v[58:61]
	v_mfma_f32_16x16x32_bf16 v[38:41], v[130:133], v[206:209], v[38:41]
	v_mfma_f32_16x16x32_bf16 v[34:37], v[138:141], v[206:209], v[34:37]
	v_mfma_f32_16x16x32_bf16 v[22:25], v[130:133], v[214:217], v[22:25]
	v_mfma_f32_16x16x32_bf16 v[18:21], v[138:141], v[214:217], v[18:21]
	v_mfma_f32_16x16x32_bf16 v[6:9], v[130:133], v[222:225], v[6:9]
	v_mfma_f32_16x16x32_bf16 v[2:5], v[138:141], v[222:225], v[2:5]
	v_mfma_f32_16x16x32_bf16 v[62:65], v[134:137], v[202:205], v[62:65]
	v_mfma_f32_16x16x32_bf16 v[58:61], v[142:145], v[202:205], v[58:61]
	v_mfma_f32_16x16x32_bf16 v[38:41], v[134:137], v[210:213], v[38:41]
	v_mfma_f32_16x16x32_bf16 v[34:37], v[142:145], v[210:213], v[34:37]
	v_mfma_f32_16x16x32_bf16 v[22:25], v[134:137], v[218:221], v[22:25]
	v_mfma_f32_16x16x32_bf16 v[18:21], v[142:145], v[218:221], v[18:21]
	v_mfma_f32_16x16x32_bf16 v[6:9], v[134:137], v[226:229], v[6:9]
	v_mfma_f32_16x16x32_bf16 v[2:5], v[142:145], v[226:229], v[2:5]
	s_setprio 0
	s_setprio 1
	v_mfma_f32_16x16x32_bf16 v[78:81], v[168:171], v[198:201], v[78:81]
	v_mfma_f32_16x16x32_bf16 v[74:77], v[176:179], v[198:201], v[74:77]
	v_mfma_f32_16x16x32_bf16 v[46:49], v[168:171], v[206:209], v[46:49]
	v_mfma_f32_16x16x32_bf16 v[42:45], v[176:179], v[206:209], v[42:45]
	v_mfma_f32_16x16x32_bf16 v[30:33], v[168:171], v[214:217], v[30:33]
	v_mfma_f32_16x16x32_bf16 v[26:29], v[176:179], v[214:217], v[26:29]
	v_mfma_f32_16x16x32_bf16 v[14:17], v[168:171], v[222:225], v[14:17]
	v_mfma_f32_16x16x32_bf16 v[10:13], v[176:179], v[222:225], v[10:13]
	v_mfma_f32_16x16x32_bf16 v[78:81], v[172:175], v[202:205], v[78:81]
	v_mfma_f32_16x16x32_bf16 v[74:77], v[180:183], v[202:205], v[74:77]
	v_mfma_f32_16x16x32_bf16 v[46:49], v[172:175], v[210:213], v[46:49]
	v_mfma_f32_16x16x32_bf16 v[42:45], v[180:183], v[210:213], v[42:45]
	v_mfma_f32_16x16x32_bf16 v[30:33], v[172:175], v[218:221], v[30:33]
	v_mfma_f32_16x16x32_bf16 v[26:29], v[180:183], v[218:221], v[26:29]
	v_mfma_f32_16x16x32_bf16 v[14:17], v[172:175], v[226:229], v[14:17]
	v_mfma_f32_16x16x32_bf16 v[10:13], v[180:183], v[226:229], v[10:13]
	s_barrier
	s_setprio 0
	s_add_u32 s40, s40, 0x100
	s_addc_u32 s49, s49, 0
	s_add_u32 s10, s10, 0x100
	s_addc_u32 s11, s11, 0
	s_cmp_ge_u32 vcc_lo, s19
	s_mov_b32 s38, vcc_lo
	s_cbranch_scc0 .LBB0_262
	v_readlane_b32 s10, v254, 27
	v_readlane_b32 s11, v254, 28
	s_and_b64 vcc, exec, s[10:11]
	s_cbranch_vccz .LBB0_270
	s_barrier
	s_cmp_lt_i32 s18, 0
	s_mov_b64 s[10:11], -1
	s_cbranch_scc1 .LBB0_271

.LBB0_1693:
	ds_read_b128 v[128:131], v169
	ds_read_b128 v[132:135], v169 offset:1024
	ds_read_b128 v[136:139], v169 offset:2048
	ds_read_b128 v[140:143], v169 offset:3072
	ds_read_b128 v[158:161], v170
	ds_read_b128 v[162:165], v170 offset:1024
	ds_read_b128 v[172:175], v170 offset:2048
	ds_read_b128 v[176:179], v170 offset:3072
	s_add_u32 s24, s22, 0xfff80080
	s_addc_u32 s25, s23, -1
	s_cmp_eq_u32 s36, 4
	s_cselect_b32 s27, s5, s25
	s_cselect_b32 s26, s4, s24
	s_cselect_b32 s25, s13, s35
	s_cselect_b32 s24, s15, s34
	v_lshl_add_u64 v[212:213], s[22:23], 0, v[152:153]
	s_add_i32 m0, s94, 0xc000
	ds_read_b128 v[180:183], v171
	ds_read_b128 v[184:187], v171 offset:1024
	ds_read_b128 v[188:191], v171 offset:2048
	ds_read_b128 v[192:195], v171 offset:3072
	ds_read_b128 v[196:199], v171 offset:4096
	ds_read_b128 v[200:203], v171 offset:5120
	ds_read_b128 v[204:207], v171 offset:6144
	ds_read_b128 v[208:211], v171 offset:7168
	global_load_lds_dwordx4 v[212:213], off sc0
	v_lshl_add_u64 v[212:213], s[22:23], 0, v[154:155]
	s_add_i32 m0, s94, 0xe000
	s_nop 0
	global_load_lds_dwordx4 v[212:213], off sc0
	s_waitcnt vmcnt(8)
	s_waitcnt lgkmcnt(0)
	s_setprio 1
	s_barrier
	v_mfma_f32_16x16x32_bf16 v[80:83], v[128:131], v[180:183], v[80:83]
	v_mfma_f32_16x16x32_bf16 v[92:95], v[136:139], v[180:183], v[92:95]
	v_mfma_f32_16x16x32_bf16 v[84:87], v[128:131], v[188:191], v[84:87]
	v_mfma_f32_16x16x32_bf16 v[96:99], v[136:139], v[188:191], v[96:99]
	v_mfma_f32_16x16x32_bf16 v[88:91], v[128:131], v[196:199], v[88:91]
	v_mfma_f32_16x16x32_bf16 v[100:103], v[136:139], v[196:199], v[100:103]
	v_mfma_f32_16x16x32_bf16 v[72:75], v[128:131], v[204:207], v[72:75]
	v_mfma_f32_16x16x32_bf16 v[76:79], v[136:139], v[204:207], v[76:79]
	v_mfma_f32_16x16x32_bf16 v[80:83], v[132:135], v[184:187], v[80:83]
	v_mfma_f32_16x16x32_bf16 v[92:95], v[140:143], v[184:187], v[92:95]
	v_mfma_f32_16x16x32_bf16 v[84:87], v[132:135], v[192:195], v[84:87]
	v_mfma_f32_16x16x32_bf16 v[96:99], v[140:143], v[192:195], v[96:99]
	v_mfma_f32_16x16x32_bf16 v[88:91], v[132:135], v[200:203], v[88:91]
	v_mfma_f32_16x16x32_bf16 v[100:103], v[140:143], v[200:203], v[100:103]
	v_mfma_f32_16x16x32_bf16 v[72:75], v[132:135], v[208:211], v[72:75]
	v_mfma_f32_16x16x32_bf16 v[76:79], v[140:143], v[208:211], v[76:79]
	s_setprio 0
	s_setprio 1
	v_mfma_f32_16x16x32_bf16 v[104:107], v[158:161], v[180:183], v[104:107]
	v_mfma_f32_16x16x32_bf16 v[116:119], v[172:175], v[180:183], v[116:119]
	v_mfma_f32_16x16x32_bf16 v[108:111], v[158:161], v[188:191], v[108:111]
	v_mfma_f32_16x16x32_bf16 v[120:123], v[172:175], v[188:191], v[120:123]
	v_mfma_f32_16x16x32_bf16 v[112:115], v[158:161], v[196:199], v[112:115]
	v_mfma_f32_16x16x32_bf16 v[124:127], v[172:175], v[196:199], v[124:127]
	v_mfma_f32_16x16x32_bf16 v[68:71], v[158:161], v[204:207], v[68:71]
	v_mfma_f32_16x16x32_bf16 v[64:67], v[172:175], v[204:207], v[64:67]
	v_mfma_f32_16x16x32_bf16 v[104:107], v[162:165], v[184:187], v[104:107]
	v_mfma_f32_16x16x32_bf16 v[116:119], v[176:179], v[184:187], v[116:119]
	v_mfma_f32_16x16x32_bf16 v[108:111], v[162:165], v[192:195], v[108:111]
	v_mfma_f32_16x16x32_bf16 v[120:123], v[176:179], v[192:195], v[120:123]
	v_mfma_f32_16x16x32_bf16 v[112:115], v[162:165], v[200:203], v[112:115]
	v_mfma_f32_16x16x32_bf16 v[124:127], v[176:179], v[200:203], v[124:127]
	v_mfma_f32_16x16x32_bf16 v[68:71], v[162:165], v[208:211], v[68:71]
	v_mfma_f32_16x16x32_bf16 v[64:67], v[176:179], v[208:211], v[64:67]
	s_barrier
	s_setprio 0
	s_add_i32 s37, s31, s97
	v_lshl_add_u64 v[212:213], s[24:25], 0, v[148:149]
	s_mov_b32 m0, s37
	ds_read_b128 v[180:183], v171 offset:16384
	ds_read_b128 v[184:187], v171 offset:17408
	ds_read_b128 v[188:191], v171 offset:18432
	ds_read_b128 v[192:195], v171 offset:19456
	ds_read_b128 v[196:199], v171 offset:20480
	ds_read_b128 v[200:203], v171 offset:21504
	ds_read_b128 v[204:207], v171 offset:22528
	ds_read_b128 v[208:211], v171 offset:23552
	global_load_lds_dwordx4 v[212:213], off sc0
	s_add_i32 m0, s37, 0x2000
	s_add_u32 s38, s24, 0x20000
	v_lshl_add_u64 v[214:215], s[24:25], 0, v[144:145]
	s_addc_u32 s39, s25, 0
	s_add_i32 s37, s33, s97
	global_load_lds_dwordx4 v[214:215], off sc0
	v_lshl_add_u64 v[216:217], s[38:39], 0, v[148:149]
	s_mov_b32 m0, s37
	v_lshl_add_u64 v[218:219], s[26:27], 0, v[146:147]
	global_load_lds_dwordx4 v[216:217], off sc0
	v_lshl_add_u64 v[216:217], s[38:39], 0, v[144:145]
	s_add_i32 m0, s37, 0x2000
	s_nop 0
	global_load_lds_dwordx4 v[216:217], off sc0
	v_lshl_add_u64 v[216:217], s[26:27], 0, v[150:151]
	s_mov_b32 m0, s94
	s_nop 0
	global_load_lds_dwordx4 v[216:217], off sc0
	s_mov_b32 m0, s3
	s_nop 0
	global_load_lds_dwordx4 v[218:219], off sc0
	s_waitcnt vmcnt(8)
	s_waitcnt lgkmcnt(0)
	s_setprio 1
	s_barrier
	v_mfma_f32_16x16x32_bf16 v[48:51], v[128:131], v[180:183], v[48:51]
	v_mfma_f32_16x16x32_bf16 v[52:55], v[136:139], v[180:183], v[52:55]
	v_mfma_f32_16x16x32_bf16 v[32:35], v[128:131], v[188:191], v[32:35]
	v_mfma_f32_16x16x32_bf16 v[36:39], v[136:139], v[188:191], v[36:39]
	v_mfma_f32_16x16x32_bf16 v[16:19], v[128:131], v[196:199], v[16:19]
	v_mfma_f32_16x16x32_bf16 v[20:23], v[136:139], v[196:199], v[20:23]
	v_mfma_f32_16x16x32_bf16 v[0:3], v[128:131], v[204:207], v[0:3]
	v_mfma_f32_16x16x32_bf16 v[4:7], v[136:139], v[204:207], v[4:7]
	v_mfma_f32_16x16x32_bf16 v[48:51], v[132:135], v[184:187], v[48:51]
	v_mfma_f32_16x16x32_bf16 v[52:55], v[140:143], v[184:187], v[52:55]
	v_mfma_f32_16x16x32_bf16 v[32:35], v[132:135], v[192:195], v[32:35]
	v_mfma_f32_16x16x32_bf16 v[36:39], v[140:143], v[192:195], v[36:39]
	v_mfma_f32_16x16x32_bf16 v[16:19], v[132:135], v[200:203], v[16:19]
	v_mfma_f32_16x16x32_bf16 v[20:23], v[140:143], v[200:203], v[20:23]
	v_mfma_f32_16x16x32_bf16 v[0:3], v[132:135], v[208:211], v[0:3]
	v_mfma_f32_16x16x32_bf16 v[4:7], v[140:143], v[208:211], v[4:7]
	s_setprio 0
	s_setprio 1
	v_mfma_f32_16x16x32_bf16 v[56:59], v[158:161], v[180:183], v[56:59]
	v_mfma_f32_16x16x32_bf16 v[60:63], v[172:175], v[180:183], v[60:63]
	v_mfma_f32_16x16x32_bf16 v[40:43], v[158:161], v[188:191], v[40:43]
	v_mfma_f32_16x16x32_bf16 v[44:47], v[172:175], v[188:191], v[44:47]
	v_mfma_f32_16x16x32_bf16 v[24:27], v[158:161], v[196:199], v[24:27]
	v_mfma_f32_16x16x32_bf16 v[28:31], v[172:175], v[196:199], v[28:31]
	v_mfma_f32_16x16x32_bf16 v[8:11], v[158:161], v[204:207], v[8:11]
	v_mfma_f32_16x16x32_bf16 v[12:15], v[172:175], v[204:207], v[12:15]
	v_mfma_f32_16x16x32_bf16 v[56:59], v[162:165], v[184:187], v[56:59]
	v_mfma_f32_16x16x32_bf16 v[60:63], v[176:179], v[184:187], v[60:63]
	v_mfma_f32_16x16x32_bf16 v[40:43], v[162:165], v[192:195], v[40:43]
	v_mfma_f32_16x16x32_bf16 v[44:47], v[176:179], v[192:195], v[44:47]
	v_mfma_f32_16x16x32_bf16 v[24:27], v[162:165], v[200:203], v[24:27]
	v_mfma_f32_16x16x32_bf16 v[28:31], v[176:179], v[200:203], v[28:31]
	v_mfma_f32_16x16x32_bf16 v[8:11], v[162:165], v[208:211], v[8:11]
	v_mfma_f32_16x16x32_bf16 v[12:15], v[176:179], v[208:211], v[12:15]
	s_barrier
	s_setprio 0
	s_add_i32 s37, 0, 0x18000
	s_add_i32 s38, 0, 0x1c000
	v_add_u32_e32 v140, s37, v167
	v_add_u32_e32 v176, s38, v167
	ds_read_b128 v[128:131], v140
	ds_read_b128 v[132:135], v140 offset:1024
	ds_read_b128 v[136:139], v140 offset:2048
	ds_read_b128 v[140:143], v140 offset:3072
	ds_read_b128 v[158:161], v176
	ds_read_b128 v[162:165], v176 offset:1024
	ds_read_b128 v[172:175], v176 offset:2048
	ds_read_b128 v[176:179], v176 offset:3072
	s_add_u32 s26, s26, 0x80000
	s_addc_u32 s27, s27, 0
	s_mov_b32 m0, s7
	v_lshl_add_u64 v[220:221], s[26:27], 0, v[150:151]
	ds_read_b128 v[180:183], v171 offset:32768
	ds_read_b128 v[184:187], v171 offset:33792
	ds_read_b128 v[188:191], v171 offset:34816
	ds_read_b128 v[192:195], v171 offset:35840
	ds_read_b128 v[196:199], v171 offset:36864
	ds_read_b128 v[200:203], v171 offset:37888
	ds_read_b128 v[204:207], v171 offset:38912
	ds_read_b128 v[208:211], v171 offset:39936
	global_load_lds_dwordx4 v[220:221], off sc0
	v_lshl_add_u64 v[220:221], s[26:27], 0, v[146:147]
	s_mov_b32 m0, s19
	s_nop 0
	global_load_lds_dwordx4 v[220:221], off sc0
	s_waitcnt vmcnt(8)
	s_waitcnt lgkmcnt(0)
	s_setprio 1
	s_barrier
	v_mfma_f32_16x16x32_bf16 v[80:83], v[128:131], v[180:183], v[80:83]
	v_mfma_f32_16x16x32_bf16 v[92:95], v[136:139], v[180:183], v[92:95]
	v_mfma_f32_16x16x32_bf16 v[84:87], v[128:131], v[188:191], v[84:87]
	v_mfma_f32_16x16x32_bf16 v[96:99], v[136:139], v[188:191], v[96:99]
	v_mfma_f32_16x16x32_bf16 v[88:91], v[128:131], v[196:199], v[88:91]
	v_mfma_f32_16x16x32_bf16 v[100:103], v[136:139], v[196:199], v[100:103]
	v_mfma_f32_16x16x32_bf16 v[72:75], v[128:131], v[204:207], v[72:75]
	v_mfma_f32_16x16x32_bf16 v[76:79], v[136:139], v[204:207], v[76:79]
	v_mfma_f32_16x16x32_bf16 v[80:83], v[132:135], v[184:187], v[80:83]
	v_mfma_f32_16x16x32_bf16 v[92:95], v[140:143], v[184:187], v[92:95]
	v_mfma_f32_16x16x32_bf16 v[84:87], v[132:135], v[192:195], v[84:87]
	v_mfma_f32_16x16x32_bf16 v[96:99], v[140:143], v[192:195], v[96:99]
	v_mfma_f32_16x16x32_bf16 v[88:91], v[132:135], v[200:203], v[88:91]
	v_mfma_f32_16x16x32_bf16 v[100:103], v[140:143], v[200:203], v[100:103]
	v_mfma_f32_16x16x32_bf16 v[72:75], v[132:135], v[208:211], v[72:75]
	v_mfma_f32_16x16x32_bf16 v[76:79], v[140:143], v[208:211], v[76:79]
	s_setprio 0
	s_setprio 1
	v_mfma_f32_16x16x32_bf16 v[104:107], v[158:161], v[180:183], v[104:107]
	v_mfma_f32_16x16x32_bf16 v[116:119], v[172:175], v[180:183], v[116:119]
	v_mfma_f32_16x16x32_bf16 v[108:111], v[158:161], v[188:191], v[108:111]
	v_mfma_f32_16x16x32_bf16 v[120:123], v[172:175], v[188:191], v[120:123]
	v_mfma_f32_16x16x32_bf16 v[112:115], v[158:161], v[196:199], v[112:115]
	v_mfma_f32_16x16x32_bf16 v[124:127], v[172:175], v[196:199], v[124:127]
	v_mfma_f32_16x16x32_bf16 v[68:71], v[158:161], v[204:207], v[68:71]
	v_mfma_f32_16x16x32_bf16 v[64:67], v[172:175], v[204:207], v[64:67]
	v_mfma_f32_16x16x32_bf16 v[104:107], v[162:165], v[184:187], v[104:107]
	v_mfma_f32_16x16x32_bf16 v[116:119], v[176:179], v[184:187], v[116:119]
	v_mfma_f32_16x16x32_bf16 v[108:111], v[162:165], v[192:195], v[108:111]
	v_mfma_f32_16x16x32_bf16 v[120:123], v[176:179], v[192:195], v[120:123]
	v_mfma_f32_16x16x32_bf16 v[112:115], v[162:165], v[200:203], v[112:115]
	v_mfma_f32_16x16x32_bf16 v[124:127], v[176:179], v[200:203], v[124:127]
	v_mfma_f32_16x16x32_bf16 v[68:71], v[162:165], v[208:211], v[68:71]
	v_mfma_f32_16x16x32_bf16 v[64:67], v[176:179], v[208:211], v[64:67]
	s_barrier
	s_setprio 0
	s_add_i32 s26, s37, s97
	v_lshl_add_u64 v[212:213], v[212:213], 0, s[0:1]
	s_mov_b32 m0, s26
	ds_read_b128 v[180:183], v171 offset:49152
	ds_read_b128 v[184:187], v171 offset:50176
	ds_read_b128 v[188:191], v171 offset:51200
	ds_read_b128 v[192:195], v171 offset:52224
	ds_read_b128 v[196:199], v171 offset:53248
	ds_read_b128 v[200:203], v171 offset:54272
	ds_read_b128 v[204:207], v171 offset:55296
	ds_read_b128 v[208:211], v171 offset:56320
	global_load_lds_dwordx4 v[212:213], off sc0
	s_add_i32 m0, s26, 0x2000
	s_add_u32 s24, s24, 0x20080
	v_lshl_add_u64 v[212:213], v[214:215], 0, s[0:1]
	s_addc_u32 s25, s25, 0
	s_add_i32 s26, s38, s97
	global_load_lds_dwordx4 v[212:213], off sc0
	v_lshl_add_u64 v[212:213], s[24:25], 0, v[148:149]
	s_mov_b32 m0, s26
	s_nop 0
	global_load_lds_dwordx4 v[212:213], off sc0
	v_lshl_add_u64 v[212:213], s[24:25], 0, v[144:145]
	s_add_i32 m0, s26, 0x2000
	s_nop 0
	global_load_lds_dwordx4 v[212:213], off sc0
	v_lshl_add_u64 v[212:213], v[216:217], 0, s[0:1]
	s_mov_b32 m0, s28
	s_nop 0
	global_load_lds_dwordx4 v[212:213], off sc0
	v_lshl_add_u64 v[212:213], v[218:219], 0, s[0:1]
	s_mov_b32 m0, s29
	s_nop 0
	global_load_lds_dwordx4 v[212:213], off sc0
	s_waitcnt vmcnt(8)
	s_waitcnt lgkmcnt(0)
	s_setprio 1
	s_barrier
	v_mfma_f32_16x16x32_bf16 v[48:51], v[128:131], v[180:183], v[48:51]
	v_mfma_f32_16x16x32_bf16 v[52:55], v[136:139], v[180:183], v[52:55]
	v_mfma_f32_16x16x32_bf16 v[32:35], v[128:131], v[188:191], v[32:35]
	v_mfma_f32_16x16x32_bf16 v[36:39], v[136:139], v[188:191], v[36:39]
	v_mfma_f32_16x16x32_bf16 v[16:19], v[128:131], v[196:199], v[16:19]
	v_mfma_f32_16x16x32_bf16 v[20:23], v[136:139], v[196:199], v[20:23]
	v_mfma_f32_16x16x32_bf16 v[0:3], v[128:131], v[204:207], v[0:3]
	v_mfma_f32_16x16x32_bf16 v[4:7], v[136:139], v[204:207], v[4:7]
	v_mfma_f32_16x16x32_bf16 v[48:51], v[132:135], v[184:187], v[48:51]
	v_mfma_f32_16x16x32_bf16 v[52:55], v[140:143], v[184:187], v[52:55]
	v_mfma_f32_16x16x32_bf16 v[32:35], v[132:135], v[192:195], v[32:35]
	v_mfma_f32_16x16x32_bf16 v[36:39], v[140:143], v[192:195], v[36:39]
	v_mfma_f32_16x16x32_bf16 v[16:19], v[132:135], v[200:203], v[16:19]
	v_mfma_f32_16x16x32_bf16 v[20:23], v[140:143], v[200:203], v[20:23]
	v_mfma_f32_16x16x32_bf16 v[0:3], v[132:135], v[208:211], v[0:3]
	v_mfma_f32_16x16x32_bf16 v[4:7], v[140:143], v[208:211], v[4:7]
	s_setprio 0
	s_setprio 1
	v_mfma_f32_16x16x32_bf16 v[56:59], v[158:161], v[180:183], v[56:59]
	v_mfma_f32_16x16x32_bf16 v[60:63], v[172:175], v[180:183], v[60:63]
	v_mfma_f32_16x16x32_bf16 v[40:43], v[158:161], v[188:191], v[40:43]
	v_mfma_f32_16x16x32_bf16 v[44:47], v[172:175], v[188:191], v[44:47]
	v_mfma_f32_16x16x32_bf16 v[24:27], v[158:161], v[196:199], v[24:27]
	v_mfma_f32_16x16x32_bf16 v[28:31], v[172:175], v[196:199], v[28:31]
	v_mfma_f32_16x16x32_bf16 v[8:11], v[158:161], v[204:207], v[8:11]
	v_mfma_f32_16x16x32_bf16 v[12:15], v[172:175], v[204:207], v[12:15]
	v_mfma_f32_16x16x32_bf16 v[56:59], v[162:165], v[184:187], v[56:59]
	v_mfma_f32_16x16x32_bf16 v[60:63], v[176:179], v[184:187], v[60:63]
	v_mfma_f32_16x16x32_bf16 v[40:43], v[162:165], v[192:195], v[40:43]
	v_mfma_f32_16x16x32_bf16 v[44:47], v[176:179], v[192:195], v[44:47]
	v_mfma_f32_16x16x32_bf16 v[24:27], v[162:165], v[200:203], v[24:27]
	v_mfma_f32_16x16x32_bf16 v[28:31], v[176:179], v[200:203], v[28:31]
	v_mfma_f32_16x16x32_bf16 v[8:11], v[162:165], v[208:211], v[8:11]
	v_mfma_f32_16x16x32_bf16 v[12:15], v[176:179], v[208:211], v[12:15]
	s_barrier
	s_setprio 0
	s_add_i32 s36, s36, 2
	s_add_u32 s34, s34, 0x100
	s_addc_u32 s35, s35, 0
	s_add_u32 s22, s22, 0x100
	s_addc_u32 s23, s23, 0
	s_cmp_gt_u32 s36, 5
	s_cbranch_scc0 .LBB0_1693
	v_readlane_b32 s22, v254, 27
	v_readlane_b32 s23, v254, 28
	s_and_b64 vcc, exec, s[22:23]
	s_cbranch_vccz .LBB0_1696
	s_barrier

.LBB0_2020:
	ds_read_b128 v[128:131], v244
	ds_read_b128 v[132:135], v244 offset:1024
	ds_read_b128 v[136:139], v244 offset:2048
	ds_read_b128 v[140:143], v244 offset:3072
	ds_read_b128 v[144:147], v245
	ds_read_b128 v[148:151], v245 offset:1024
	ds_read_b128 v[152:155], v245 offset:2048
	ds_read_b128 v[156:159], v245 offset:3072
	s_add_i32 s71, s46, 2
	s_add_u32 s47, s44, 0xfff00080
	s_addc_u32 s48, s45, -1
	s_cmp_eq_u32 s68, s46
	s_cselect_b32 s46, s43, s69
	s_cselect_b32 s49, s5, s48
	s_cselect_b32 s48, s23, s47
	s_cselect_b32 s47, s21, s70
	v_lshl_add_u64 v[192:193], s[44:45], 0, v[218:219]
	s_add_i32 m0, s94, 0xc000
	ds_read_b128 v[160:163], v246
	ds_read_b128 v[164:167], v246 offset:1024
	ds_read_b128 v[168:171], v246 offset:2048
	ds_read_b128 v[172:175], v246 offset:3072
	ds_read_b128 v[176:179], v246 offset:4096
	ds_read_b128 v[180:183], v246 offset:5120
	ds_read_b128 v[184:187], v246 offset:6144
	ds_read_b128 v[188:191], v246 offset:7168
	global_load_lds_dwordx4 v[192:193], off sc0
	v_lshl_add_u64 v[192:193], s[44:45], 0, v[220:221]
	s_add_i32 m0, s94, 0xe000
	s_nop 0
	global_load_lds_dwordx4 v[192:193], off sc0
	s_waitcnt vmcnt(8)
	s_waitcnt lgkmcnt(0)
	s_setprio 1
	s_barrier
	v_mfma_f32_16x16x32_bf16 v[112:115], v[128:131], v[160:163], v[112:115]
	v_mfma_f32_16x16x32_bf16 v[116:119], v[136:139], v[160:163], v[116:119]
	v_mfma_f32_16x16x32_bf16 v[100:103], v[128:131], v[168:171], v[100:103]
	v_mfma_f32_16x16x32_bf16 v[96:99], v[136:139], v[168:171], v[96:99]
	v_mfma_f32_16x16x32_bf16 v[84:87], v[128:131], v[176:179], v[84:87]
	v_mfma_f32_16x16x32_bf16 v[80:83], v[136:139], v[176:179], v[80:83]
	v_mfma_f32_16x16x32_bf16 v[52:55], v[128:131], v[184:187], v[52:55]
	v_mfma_f32_16x16x32_bf16 v[48:51], v[136:139], v[184:187], v[48:51]
	v_mfma_f32_16x16x32_bf16 v[112:115], v[132:135], v[164:167], v[112:115]
	v_mfma_f32_16x16x32_bf16 v[116:119], v[140:143], v[164:167], v[116:119]
	v_mfma_f32_16x16x32_bf16 v[100:103], v[132:135], v[172:175], v[100:103]
	v_mfma_f32_16x16x32_bf16 v[96:99], v[140:143], v[172:175], v[96:99]
	v_mfma_f32_16x16x32_bf16 v[84:87], v[132:135], v[180:183], v[84:87]
	v_mfma_f32_16x16x32_bf16 v[80:83], v[140:143], v[180:183], v[80:83]
	v_mfma_f32_16x16x32_bf16 v[52:55], v[132:135], v[188:191], v[52:55]
	v_mfma_f32_16x16x32_bf16 v[48:51], v[140:143], v[188:191], v[48:51]
	s_setprio 0
	s_setprio 1
	v_mfma_f32_16x16x32_bf16 v[124:127], v[144:147], v[160:163], v[124:127]
	v_mfma_f32_16x16x32_bf16 v[120:123], v[152:155], v[160:163], v[120:123]
	v_mfma_f32_16x16x32_bf16 v[108:111], v[144:147], v[168:171], v[108:111]
	v_mfma_f32_16x16x32_bf16 v[104:107], v[152:155], v[168:171], v[104:107]
	v_mfma_f32_16x16x32_bf16 v[92:95], v[144:147], v[176:179], v[92:95]
	v_mfma_f32_16x16x32_bf16 v[88:91], v[152:155], v[176:179], v[88:91]
	v_mfma_f32_16x16x32_bf16 v[68:71], v[144:147], v[184:187], v[68:71]
	v_mfma_f32_16x16x32_bf16 v[64:67], v[152:155], v[184:187], v[64:67]
	v_mfma_f32_16x16x32_bf16 v[124:127], v[148:151], v[164:167], v[124:127]
	v_mfma_f32_16x16x32_bf16 v[120:123], v[156:159], v[164:167], v[120:123]
	v_mfma_f32_16x16x32_bf16 v[108:111], v[148:151], v[172:175], v[108:111]
	v_mfma_f32_16x16x32_bf16 v[104:107], v[156:159], v[172:175], v[104:107]
	v_mfma_f32_16x16x32_bf16 v[92:95], v[148:151], v[180:183], v[92:95]
	v_mfma_f32_16x16x32_bf16 v[88:91], v[156:159], v[180:183], v[88:91]
	v_mfma_f32_16x16x32_bf16 v[68:71], v[148:151], v[188:191], v[68:71]
	v_mfma_f32_16x16x32_bf16 v[64:67], v[156:159], v[188:191], v[64:67]
	s_barrier
	s_setprio 0
	s_add_i32 s76, s60, s97
	v_lshl_add_u64 v[192:193], s[46:47], 0, v[210:211]
	s_mov_b32 m0, s76
	ds_read_b128 v[160:163], v246 offset:16384
	ds_read_b128 v[164:167], v246 offset:17408
	ds_read_b128 v[168:171], v246 offset:18432
	ds_read_b128 v[172:175], v246 offset:19456
	ds_read_b128 v[176:179], v246 offset:20480
	ds_read_b128 v[180:183], v246 offset:21504
	ds_read_b128 v[184:187], v246 offset:22528
	ds_read_b128 v[188:191], v246 offset:23552
	global_load_lds_dwordx4 v[192:193], off sc0
	s_add_i32 m0, s76, 0x2000
	s_add_u32 s76, s46, 0x100000
	v_lshl_add_u64 v[194:195], s[46:47], 0, v[214:215]
	s_addc_u32 s77, s47, 0
	s_add_i32 s78, s61, s97
	global_load_lds_dwordx4 v[194:195], off sc0
	v_lshl_add_u64 v[196:197], s[76:77], 0, v[210:211]
	s_mov_b32 m0, s78
	v_lshl_add_u64 v[198:199], s[48:49], 0, v[212:213]
	global_load_lds_dwordx4 v[196:197], off sc0
	v_lshl_add_u64 v[196:197], s[76:77], 0, v[214:215]
	s_add_i32 m0, s78, 0x2000
	s_nop 0
	global_load_lds_dwordx4 v[196:197], off sc0
	v_lshl_add_u64 v[196:197], s[48:49], 0, v[208:209]
	s_mov_b32 m0, s94
	s_nop 0
	global_load_lds_dwordx4 v[196:197], off sc0
	s_mov_b32 m0, s2
	s_nop 0
	global_load_lds_dwordx4 v[198:199], off sc0
	s_waitcnt vmcnt(8)
	s_waitcnt lgkmcnt(0)
	s_setprio 1
	s_barrier
	v_mfma_f32_16x16x32_bf16 v[60:63], v[128:131], v[160:163], v[60:63]
	v_mfma_f32_16x16x32_bf16 v[56:59], v[136:139], v[160:163], v[56:59]
	v_mfma_f32_16x16x32_bf16 v[36:39], v[128:131], v[168:171], v[36:39]
	v_mfma_f32_16x16x32_bf16 v[32:35], v[136:139], v[168:171], v[32:35]
	v_mfma_f32_16x16x32_bf16 v[20:23], v[128:131], v[176:179], v[20:23]
	v_mfma_f32_16x16x32_bf16 v[16:19], v[136:139], v[176:179], v[16:19]
	v_mfma_f32_16x16x32_bf16 v[4:7], v[128:131], v[184:187], v[4:7]
	v_mfma_f32_16x16x32_bf16 v[0:3], v[136:139], v[184:187], v[0:3]
	v_mfma_f32_16x16x32_bf16 v[60:63], v[132:135], v[164:167], v[60:63]
	v_mfma_f32_16x16x32_bf16 v[56:59], v[140:143], v[164:167], v[56:59]
	v_mfma_f32_16x16x32_bf16 v[36:39], v[132:135], v[172:175], v[36:39]
	v_mfma_f32_16x16x32_bf16 v[32:35], v[140:143], v[172:175], v[32:35]
	v_mfma_f32_16x16x32_bf16 v[20:23], v[132:135], v[180:183], v[20:23]
	v_mfma_f32_16x16x32_bf16 v[16:19], v[140:143], v[180:183], v[16:19]
	v_mfma_f32_16x16x32_bf16 v[4:7], v[132:135], v[188:191], v[4:7]
	v_mfma_f32_16x16x32_bf16 v[0:3], v[140:143], v[188:191], v[0:3]
	s_setprio 0
	s_setprio 1
	v_mfma_f32_16x16x32_bf16 v[76:79], v[144:147], v[160:163], v[76:79]
	v_mfma_f32_16x16x32_bf16 v[72:75], v[152:155], v[160:163], v[72:75]
	v_mfma_f32_16x16x32_bf16 v[44:47], v[144:147], v[168:171], v[44:47]
	v_mfma_f32_16x16x32_bf16 v[40:43], v[152:155], v[168:171], v[40:43]
	v_mfma_f32_16x16x32_bf16 v[28:31], v[144:147], v[176:179], v[28:31]
	v_mfma_f32_16x16x32_bf16 v[24:27], v[152:155], v[176:179], v[24:27]
	v_mfma_f32_16x16x32_bf16 v[12:15], v[144:147], v[184:187], v[12:15]
	v_mfma_f32_16x16x32_bf16 v[8:11], v[152:155], v[184:187], v[8:11]
	v_mfma_f32_16x16x32_bf16 v[76:79], v[148:151], v[164:167], v[76:79]
	v_mfma_f32_16x16x32_bf16 v[72:75], v[156:159], v[164:167], v[72:75]
	v_mfma_f32_16x16x32_bf16 v[44:47], v[148:151], v[172:175], v[44:47]
	v_mfma_f32_16x16x32_bf16 v[40:43], v[156:159], v[172:175], v[40:43]
	v_mfma_f32_16x16x32_bf16 v[28:31], v[148:151], v[180:183], v[28:31]
	v_mfma_f32_16x16x32_bf16 v[24:27], v[156:159], v[180:183], v[24:27]
	v_mfma_f32_16x16x32_bf16 v[12:15], v[148:151], v[188:191], v[12:15]
	v_mfma_f32_16x16x32_bf16 v[8:11], v[156:159], v[188:191], v[8:11]
	s_barrier
	s_setprio 0
	s_add_i32 s76, 0, 0x18000
	s_add_i32 s77, 0, 0x1c000
	v_add_u32_e32 v140, s76, v243
	v_add_u32_e32 v156, s77, v243
	ds_read_b128 v[128:131], v140
	ds_read_b128 v[132:135], v140 offset:1024
	ds_read_b128 v[136:139], v140 offset:2048
	ds_read_b128 v[140:143], v140 offset:3072
	ds_read_b128 v[144:147], v156
	ds_read_b128 v[148:151], v156 offset:1024
	ds_read_b128 v[152:155], v156 offset:2048
	ds_read_b128 v[156:159], v156 offset:3072
	s_add_u32 s48, s48, 0x100000
	s_addc_u32 s49, s49, 0
	s_mov_b32 m0, s3
	v_lshl_add_u64 v[200:201], s[48:49], 0, v[208:209]
	ds_read_b128 v[160:163], v246 offset:32768
	ds_read_b128 v[164:167], v246 offset:33792
	ds_read_b128 v[168:171], v246 offset:34816
	ds_read_b128 v[172:175], v246 offset:35840
	ds_read_b128 v[176:179], v246 offset:36864
	ds_read_b128 v[180:183], v246 offset:37888
	ds_read_b128 v[184:187], v246 offset:38912
	ds_read_b128 v[188:191], v246 offset:39936
	global_load_lds_dwordx4 v[200:201], off sc0
	v_lshl_add_u64 v[200:201], s[48:49], 0, v[212:213]
	s_mov_b32 m0, s33
	s_nop 0
	global_load_lds_dwordx4 v[200:201], off sc0
	s_waitcnt vmcnt(8)
	s_waitcnt lgkmcnt(0)
	s_setprio 1
	s_barrier
	v_mfma_f32_16x16x32_bf16 v[112:115], v[128:131], v[160:163], v[112:115]
	v_mfma_f32_16x16x32_bf16 v[116:119], v[136:139], v[160:163], v[116:119]
	v_mfma_f32_16x16x32_bf16 v[100:103], v[128:131], v[168:171], v[100:103]
	v_mfma_f32_16x16x32_bf16 v[96:99], v[136:139], v[168:171], v[96:99]
	v_mfma_f32_16x16x32_bf16 v[84:87], v[128:131], v[176:179], v[84:87]
	v_mfma_f32_16x16x32_bf16 v[80:83], v[136:139], v[176:179], v[80:83]
	v_mfma_f32_16x16x32_bf16 v[52:55], v[128:131], v[184:187], v[52:55]
	v_mfma_f32_16x16x32_bf16 v[48:51], v[136:139], v[184:187], v[48:51]
	v_mfma_f32_16x16x32_bf16 v[112:115], v[132:135], v[164:167], v[112:115]
	v_mfma_f32_16x16x32_bf16 v[116:119], v[140:143], v[164:167], v[116:119]
	v_mfma_f32_16x16x32_bf16 v[100:103], v[132:135], v[172:175], v[100:103]
	v_mfma_f32_16x16x32_bf16 v[96:99], v[140:143], v[172:175], v[96:99]
	v_mfma_f32_16x16x32_bf16 v[84:87], v[132:135], v[180:183], v[84:87]
	v_mfma_f32_16x16x32_bf16 v[80:83], v[140:143], v[180:183], v[80:83]
	v_mfma_f32_16x16x32_bf16 v[52:55], v[132:135], v[188:191], v[52:55]
	v_mfma_f32_16x16x32_bf16 v[48:51], v[140:143], v[188:191], v[48:51]
	s_setprio 0
	s_setprio 1
	v_mfma_f32_16x16x32_bf16 v[124:127], v[144:147], v[160:163], v[124:127]
	v_mfma_f32_16x16x32_bf16 v[120:123], v[152:155], v[160:163], v[120:123]
	v_mfma_f32_16x16x32_bf16 v[108:111], v[144:147], v[168:171], v[108:111]
	v_mfma_f32_16x16x32_bf16 v[104:107], v[152:155], v[168:171], v[104:107]
	v_mfma_f32_16x16x32_bf16 v[92:95], v[144:147], v[176:179], v[92:95]
	v_mfma_f32_16x16x32_bf16 v[88:91], v[152:155], v[176:179], v[88:91]
	v_mfma_f32_16x16x32_bf16 v[68:71], v[144:147], v[184:187], v[68:71]
	v_mfma_f32_16x16x32_bf16 v[64:67], v[152:155], v[184:187], v[64:67]
	v_mfma_f32_16x16x32_bf16 v[124:127], v[148:151], v[164:167], v[124:127]
	v_mfma_f32_16x16x32_bf16 v[120:123], v[156:159], v[164:167], v[120:123]
	v_mfma_f32_16x16x32_bf16 v[108:111], v[148:151], v[172:175], v[108:111]
	v_mfma_f32_16x16x32_bf16 v[104:107], v[156:159], v[172:175], v[104:107]
	v_mfma_f32_16x16x32_bf16 v[92:95], v[148:151], v[180:183], v[92:95]
	v_mfma_f32_16x16x32_bf16 v[88:91], v[156:159], v[180:183], v[88:91]
	v_mfma_f32_16x16x32_bf16 v[68:71], v[148:151], v[188:191], v[68:71]
	v_mfma_f32_16x16x32_bf16 v[64:67], v[156:159], v[188:191], v[64:67]
	s_barrier
	s_setprio 0
	s_add_i32 s48, s76, s97
	v_lshl_add_u64 v[192:193], v[192:193], 0, s[16:17]
	s_mov_b32 m0, s48
	ds_read_b128 v[160:163], v246 offset:49152
	ds_read_b128 v[164:167], v246 offset:50176
	ds_read_b128 v[168:171], v246 offset:51200
	ds_read_b128 v[172:175], v246 offset:52224
	ds_read_b128 v[176:179], v246 offset:53248
	ds_read_b128 v[180:183], v246 offset:54272
	ds_read_b128 v[184:187], v246 offset:55296
	ds_read_b128 v[188:191], v246 offset:56320
	global_load_lds_dwordx4 v[192:193], off sc0
	s_add_i32 m0, s48, 0x2000
	s_add_u32 s46, s46, 0x100080
	v_lshl_add_u64 v[192:193], v[194:195], 0, s[16:17]
	s_addc_u32 s47, s47, 0
	s_add_i32 s48, s77, s97
	global_load_lds_dwordx4 v[192:193], off sc0
	v_lshl_add_u64 v[192:193], s[46:47], 0, v[210:211]
	s_mov_b32 m0, s48
	s_nop 0
	global_load_lds_dwordx4 v[192:193], off sc0
	v_lshl_add_u64 v[192:193], s[46:47], 0, v[214:215]
	s_add_i32 m0, s48, 0x2000
	s_nop 0
	global_load_lds_dwordx4 v[192:193], off sc0
	v_lshl_add_u64 v[192:193], v[196:197], 0, s[16:17]
	s_mov_b32 m0, s54
	s_nop 0
	global_load_lds_dwordx4 v[192:193], off sc0
	v_lshl_add_u64 v[192:193], v[198:199], 0, s[16:17]
	s_mov_b32 m0, s55
	s_nop 0
	global_load_lds_dwordx4 v[192:193], off sc0
	s_waitcnt vmcnt(8)
	s_waitcnt lgkmcnt(0)
	s_setprio 1
	s_barrier
	v_mfma_f32_16x16x32_bf16 v[60:63], v[128:131], v[160:163], v[60:63]
	v_mfma_f32_16x16x32_bf16 v[56:59], v[136:139], v[160:163], v[56:59]
	v_mfma_f32_16x16x32_bf16 v[36:39], v[128:131], v[168:171], v[36:39]
	v_mfma_f32_16x16x32_bf16 v[32:35], v[136:139], v[168:171], v[32:35]
	v_mfma_f32_16x16x32_bf16 v[20:23], v[128:131], v[176:179], v[20:23]
	v_mfma_f32_16x16x32_bf16 v[16:19], v[136:139], v[176:179], v[16:19]
	v_mfma_f32_16x16x32_bf16 v[4:7], v[128:131], v[184:187], v[4:7]
	v_mfma_f32_16x16x32_bf16 v[0:3], v[136:139], v[184:187], v[0:3]
	v_mfma_f32_16x16x32_bf16 v[60:63], v[132:135], v[164:167], v[60:63]
	v_mfma_f32_16x16x32_bf16 v[56:59], v[140:143], v[164:167], v[56:59]
	v_mfma_f32_16x16x32_bf16 v[36:39], v[132:135], v[172:175], v[36:39]
	v_mfma_f32_16x16x32_bf16 v[32:35], v[140:143], v[172:175], v[32:35]
	v_mfma_f32_16x16x32_bf16 v[20:23], v[132:135], v[180:183], v[20:23]
	v_mfma_f32_16x16x32_bf16 v[16:19], v[140:143], v[180:183], v[16:19]
	v_mfma_f32_16x16x32_bf16 v[4:7], v[132:135], v[188:191], v[4:7]
	v_mfma_f32_16x16x32_bf16 v[0:3], v[140:143], v[188:191], v[0:3]
	s_setprio 0
	s_setprio 1
	v_mfma_f32_16x16x32_bf16 v[76:79], v[144:147], v[160:163], v[76:79]
	v_mfma_f32_16x16x32_bf16 v[72:75], v[152:155], v[160:163], v[72:75]
	v_mfma_f32_16x16x32_bf16 v[44:47], v[144:147], v[168:171], v[44:47]
	v_mfma_f32_16x16x32_bf16 v[40:43], v[152:155], v[168:171], v[40:43]
	v_mfma_f32_16x16x32_bf16 v[28:31], v[144:147], v[176:179], v[28:31]
	v_mfma_f32_16x16x32_bf16 v[24:27], v[152:155], v[176:179], v[24:27]
	v_mfma_f32_16x16x32_bf16 v[12:15], v[144:147], v[184:187], v[12:15]
	v_mfma_f32_16x16x32_bf16 v[8:11], v[152:155], v[184:187], v[8:11]
	v_mfma_f32_16x16x32_bf16 v[76:79], v[148:151], v[164:167], v[76:79]
	v_mfma_f32_16x16x32_bf16 v[72:75], v[156:159], v[164:167], v[72:75]
	v_mfma_f32_16x16x32_bf16 v[44:47], v[148:151], v[172:175], v[44:47]
	v_mfma_f32_16x16x32_bf16 v[40:43], v[156:159], v[172:175], v[40:43]
	v_mfma_f32_16x16x32_bf16 v[28:31], v[148:151], v[180:183], v[28:31]
	v_mfma_f32_16x16x32_bf16 v[24:27], v[156:159], v[180:183], v[24:27]
	v_mfma_f32_16x16x32_bf16 v[12:15], v[148:151], v[188:191], v[12:15]
	v_mfma_f32_16x16x32_bf16 v[8:11], v[156:159], v[188:191], v[8:11]
	s_barrier
	s_setprio 0
	s_add_u32 s69, s69, 0x100
	s_addc_u32 s70, s70, 0
	s_add_u32 s44, s44, 0x100
	s_addc_u32 s45, s45, 0
	s_cmp_ge_u32 s71, s67
	s_mov_b32 s46, s71
	s_cbranch_scc0 .LBB0_2020
	v_readlane_b32 s44, v254, 27
	v_readlane_b32 s45, v254, 28
	s_and_b64 vcc, exec, s[44:45]
	s_cbranch_vccz .LBB0_2028
	s_barrier
	s_cmp_lt_i32 s14, 0
	s_mov_b64 s[44:45], -1
	s_cbranch_scc1 .LBB0_2029

.LBB0_2289:
	ds_read_b128 v[148:151], v159
	ds_read_b128 v[164:167], v159 offset:1024
	ds_read_b128 v[168:171], v159 offset:2048
	ds_read_b128 v[172:175], v159 offset:3072
	ds_read_b128 v[176:179], v160
	ds_read_b128 v[180:183], v160 offset:1024
	ds_read_b128 v[184:187], v160 offset:2048
	ds_read_b128 v[188:191], v160 offset:3072
	s_add_i32 s87, s46, 2
	s_add_u32 s47, s44, 0xfff00080
	s_addc_u32 s48, s45, -1
	s_cmp_eq_u32 s43, s46
	s_cselect_b32 s46, s25, s85
	s_cselect_b32 s49, s37, s48
	s_cselect_b32 s48, s36, s47
	s_cselect_b32 s47, s5, s86
	v_lshl_add_u64 v[152:153], s[44:45], 0, v[142:143]
	s_add_i32 m0, s94, 0xc000
	ds_read_b128 v[192:195], v161
	ds_read_b128 v[196:199], v161 offset:1024
	ds_read_b128 v[200:203], v161 offset:2048
	ds_read_b128 v[204:207], v161 offset:3072
	ds_read_b128 v[208:211], v161 offset:4096
	ds_read_b128 v[212:215], v161 offset:5120
	ds_read_b128 v[216:219], v161 offset:6144
	ds_read_b128 v[220:223], v161 offset:7168
	global_load_lds_dwordx4 v[152:153], off sc0
	v_lshl_add_u64 v[152:153], s[44:45], 0, v[144:145]
	s_add_i32 m0, s94, 0xe000
	s_nop 0
	global_load_lds_dwordx4 v[152:153], off sc0
	s_waitcnt vmcnt(8)
	s_waitcnt lgkmcnt(0)
	s_setprio 1
	s_barrier
	v_mfma_f32_16x16x32_bf16 v[112:115], v[148:151], v[192:195], v[112:115]
	v_mfma_f32_16x16x32_bf16 v[116:119], v[168:171], v[192:195], v[116:119]
	v_mfma_f32_16x16x32_bf16 v[100:103], v[148:151], v[200:203], v[100:103]
	v_mfma_f32_16x16x32_bf16 v[96:99], v[168:171], v[200:203], v[96:99]
	v_mfma_f32_16x16x32_bf16 v[84:87], v[148:151], v[208:211], v[84:87]
	v_mfma_f32_16x16x32_bf16 v[80:83], v[168:171], v[208:211], v[80:83]
	v_mfma_f32_16x16x32_bf16 v[52:55], v[148:151], v[216:219], v[52:55]
	v_mfma_f32_16x16x32_bf16 v[48:51], v[168:171], v[216:219], v[48:51]
	v_mfma_f32_16x16x32_bf16 v[112:115], v[164:167], v[196:199], v[112:115]
	v_mfma_f32_16x16x32_bf16 v[116:119], v[172:175], v[196:199], v[116:119]
	v_mfma_f32_16x16x32_bf16 v[100:103], v[164:167], v[204:207], v[100:103]
	v_mfma_f32_16x16x32_bf16 v[96:99], v[172:175], v[204:207], v[96:99]
	v_mfma_f32_16x16x32_bf16 v[84:87], v[164:167], v[212:215], v[84:87]
	v_mfma_f32_16x16x32_bf16 v[80:83], v[172:175], v[212:215], v[80:83]
	v_mfma_f32_16x16x32_bf16 v[52:55], v[164:167], v[220:223], v[52:55]
	v_mfma_f32_16x16x32_bf16 v[48:51], v[172:175], v[220:223], v[48:51]
	s_setprio 0
	s_setprio 1
	v_mfma_f32_16x16x32_bf16 v[124:127], v[176:179], v[192:195], v[124:127]
	v_mfma_f32_16x16x32_bf16 v[120:123], v[184:187], v[192:195], v[120:123]
	v_mfma_f32_16x16x32_bf16 v[108:111], v[176:179], v[200:203], v[108:111]
	v_mfma_f32_16x16x32_bf16 v[104:107], v[184:187], v[200:203], v[104:107]
	v_mfma_f32_16x16x32_bf16 v[92:95], v[176:179], v[208:211], v[92:95]
	v_mfma_f32_16x16x32_bf16 v[88:91], v[184:187], v[208:211], v[88:91]
	v_mfma_f32_16x16x32_bf16 v[68:71], v[176:179], v[216:219], v[68:71]
	v_mfma_f32_16x16x32_bf16 v[64:67], v[184:187], v[216:219], v[64:67]
	v_mfma_f32_16x16x32_bf16 v[124:127], v[180:183], v[196:199], v[124:127]
	v_mfma_f32_16x16x32_bf16 v[120:123], v[188:191], v[196:199], v[120:123]
	v_mfma_f32_16x16x32_bf16 v[108:111], v[180:183], v[204:207], v[108:111]
	v_mfma_f32_16x16x32_bf16 v[104:107], v[188:191], v[204:207], v[104:107]
	v_mfma_f32_16x16x32_bf16 v[92:95], v[180:183], v[212:215], v[92:95]
	v_mfma_f32_16x16x32_bf16 v[88:91], v[188:191], v[212:215], v[88:91]
	v_mfma_f32_16x16x32_bf16 v[68:71], v[180:183], v[220:223], v[68:71]
	v_mfma_f32_16x16x32_bf16 v[64:67], v[188:191], v[220:223], v[64:67]
	s_barrier
	s_setprio 0
	s_add_i32 s88, s77, s97
	v_lshl_add_u64 v[152:153], s[46:47], 0, v[132:133]
	s_mov_b32 m0, s88
	ds_read_b128 v[192:195], v161 offset:16384
	ds_read_b128 v[196:199], v161 offset:17408
	ds_read_b128 v[200:203], v161 offset:18432
	ds_read_b128 v[204:207], v161 offset:19456
	ds_read_b128 v[208:211], v161 offset:20480
	ds_read_b128 v[212:215], v161 offset:21504
	ds_read_b128 v[216:219], v161 offset:22528
	ds_read_b128 v[220:223], v161 offset:23552
	global_load_lds_dwordx4 v[152:153], off sc0
	s_add_i32 m0, s88, 0x2000
	s_add_u32 s88, s46, 0x100000
	v_lshl_add_u64 v[224:225], s[46:47], 0, v[136:137]
	s_addc_u32 s89, s47, 0
	s_add_i32 s90, s78, s97
	global_load_lds_dwordx4 v[224:225], off sc0
	v_lshl_add_u64 v[226:227], s[88:89], 0, v[132:133]
	s_mov_b32 m0, s90
	v_lshl_add_u64 v[228:229], s[48:49], 0, v[134:135]
	global_load_lds_dwordx4 v[226:227], off sc0
	v_lshl_add_u64 v[226:227], s[88:89], 0, v[136:137]
	s_add_i32 m0, s90, 0x2000
	s_nop 0
	global_load_lds_dwordx4 v[226:227], off sc0
	v_lshl_add_u64 v[226:227], s[48:49], 0, v[130:131]
	s_mov_b32 m0, s94
	s_nop 0
	global_load_lds_dwordx4 v[226:227], off sc0
	s_mov_b32 m0, s52
	s_nop 0
	global_load_lds_dwordx4 v[228:229], off sc0
	s_waitcnt vmcnt(8)
	s_waitcnt lgkmcnt(0)
	s_setprio 1
	s_barrier
	v_mfma_f32_16x16x32_bf16 v[60:63], v[148:151], v[192:195], v[60:63]
	v_mfma_f32_16x16x32_bf16 v[56:59], v[168:171], v[192:195], v[56:59]
	v_mfma_f32_16x16x32_bf16 v[36:39], v[148:151], v[200:203], v[36:39]
	v_mfma_f32_16x16x32_bf16 v[32:35], v[168:171], v[200:203], v[32:35]
	v_mfma_f32_16x16x32_bf16 v[20:23], v[148:151], v[208:211], v[20:23]
	v_mfma_f32_16x16x32_bf16 v[16:19], v[168:171], v[208:211], v[16:19]
	v_mfma_f32_16x16x32_bf16 v[4:7], v[148:151], v[216:219], v[4:7]
	v_mfma_f32_16x16x32_bf16 v[0:3], v[168:171], v[216:219], v[0:3]
	v_mfma_f32_16x16x32_bf16 v[60:63], v[164:167], v[196:199], v[60:63]
	v_mfma_f32_16x16x32_bf16 v[56:59], v[172:175], v[196:199], v[56:59]
	v_mfma_f32_16x16x32_bf16 v[36:39], v[164:167], v[204:207], v[36:39]
	v_mfma_f32_16x16x32_bf16 v[32:35], v[172:175], v[204:207], v[32:35]
	v_mfma_f32_16x16x32_bf16 v[20:23], v[164:167], v[212:215], v[20:23]
	v_mfma_f32_16x16x32_bf16 v[16:19], v[172:175], v[212:215], v[16:19]
	v_mfma_f32_16x16x32_bf16 v[4:7], v[164:167], v[220:223], v[4:7]
	v_mfma_f32_16x16x32_bf16 v[0:3], v[172:175], v[220:223], v[0:3]
	s_setprio 0
	s_setprio 1
	v_mfma_f32_16x16x32_bf16 v[76:79], v[176:179], v[192:195], v[76:79]
	v_mfma_f32_16x16x32_bf16 v[72:75], v[184:187], v[192:195], v[72:75]
	v_mfma_f32_16x16x32_bf16 v[44:47], v[176:179], v[200:203], v[44:47]
	v_mfma_f32_16x16x32_bf16 v[40:43], v[184:187], v[200:203], v[40:43]
	v_mfma_f32_16x16x32_bf16 v[28:31], v[176:179], v[208:211], v[28:31]
	v_mfma_f32_16x16x32_bf16 v[24:27], v[184:187], v[208:211], v[24:27]
	v_mfma_f32_16x16x32_bf16 v[12:15], v[176:179], v[216:219], v[12:15]
	v_mfma_f32_16x16x32_bf16 v[8:11], v[184:187], v[216:219], v[8:11]
	v_mfma_f32_16x16x32_bf16 v[76:79], v[180:183], v[196:199], v[76:79]
	v_mfma_f32_16x16x32_bf16 v[72:75], v[188:191], v[196:199], v[72:75]
	v_mfma_f32_16x16x32_bf16 v[44:47], v[180:183], v[204:207], v[44:47]
	v_mfma_f32_16x16x32_bf16 v[40:43], v[188:191], v[204:207], v[40:43]
	v_mfma_f32_16x16x32_bf16 v[28:31], v[180:183], v[212:215], v[28:31]
	v_mfma_f32_16x16x32_bf16 v[24:27], v[188:191], v[212:215], v[24:27]
	v_mfma_f32_16x16x32_bf16 v[12:15], v[180:183], v[220:223], v[12:15]
	v_mfma_f32_16x16x32_bf16 v[8:11], v[188:191], v[220:223], v[8:11]
	s_barrier
	s_setprio 0
	s_add_i32 s88, 0, 0x18000
	v_add_u32_e32 v163, s88, v157
	s_add_i32 s89, 0, 0x1c000
	ds_read_b128 v[148:151], v163
	ds_read_b128 v[164:167], v163 offset:1024
	ds_read_b128 v[168:171], v163 offset:2048
	ds_read_b128 v[172:175], v163 offset:3072
	v_add_u32_e32 v163, s89, v157
	ds_read_b128 v[176:179], v163
	ds_read_b128 v[180:183], v163 offset:1024
	ds_read_b128 v[184:187], v163 offset:2048
	ds_read_b128 v[188:191], v163 offset:3072
	s_add_u32 s48, s48, 0x100000
	s_addc_u32 s49, s49, 0
	s_mov_b32 m0, s53
	v_lshl_add_u64 v[230:231], s[48:49], 0, v[130:131]
	ds_read_b128 v[192:195], v161 offset:32768
	ds_read_b128 v[196:199], v161 offset:33792
	ds_read_b128 v[200:203], v161 offset:34816
	ds_read_b128 v[204:207], v161 offset:35840
	ds_read_b128 v[208:211], v161 offset:36864
	ds_read_b128 v[212:215], v161 offset:37888
	ds_read_b128 v[216:219], v161 offset:38912
	ds_read_b128 v[220:223], v161 offset:39936
	global_load_lds_dwordx4 v[230:231], off sc0
	v_lshl_add_u64 v[230:231], s[48:49], 0, v[134:135]
	s_mov_b32 m0, s54
	s_nop 0
	global_load_lds_dwordx4 v[230:231], off sc0
	s_waitcnt vmcnt(8)
	s_waitcnt lgkmcnt(0)
	s_setprio 1
	s_barrier
	v_mfma_f32_16x16x32_bf16 v[112:115], v[148:151], v[192:195], v[112:115]
	v_mfma_f32_16x16x32_bf16 v[116:119], v[168:171], v[192:195], v[116:119]
	v_mfma_f32_16x16x32_bf16 v[100:103], v[148:151], v[200:203], v[100:103]
	v_mfma_f32_16x16x32_bf16 v[96:99], v[168:171], v[200:203], v[96:99]
	v_mfma_f32_16x16x32_bf16 v[84:87], v[148:151], v[208:211], v[84:87]
	v_mfma_f32_16x16x32_bf16 v[80:83], v[168:171], v[208:211], v[80:83]
	v_mfma_f32_16x16x32_bf16 v[52:55], v[148:151], v[216:219], v[52:55]
	v_mfma_f32_16x16x32_bf16 v[48:51], v[168:171], v[216:219], v[48:51]
	v_mfma_f32_16x16x32_bf16 v[112:115], v[164:167], v[196:199], v[112:115]
	v_mfma_f32_16x16x32_bf16 v[116:119], v[172:175], v[196:199], v[116:119]
	v_mfma_f32_16x16x32_bf16 v[100:103], v[164:167], v[204:207], v[100:103]
	v_mfma_f32_16x16x32_bf16 v[96:99], v[172:175], v[204:207], v[96:99]
	v_mfma_f32_16x16x32_bf16 v[84:87], v[164:167], v[212:215], v[84:87]
	v_mfma_f32_16x16x32_bf16 v[80:83], v[172:175], v[212:215], v[80:83]
	v_mfma_f32_16x16x32_bf16 v[52:55], v[164:167], v[220:223], v[52:55]
	v_mfma_f32_16x16x32_bf16 v[48:51], v[172:175], v[220:223], v[48:51]
	s_setprio 0
	s_setprio 1
	v_mfma_f32_16x16x32_bf16 v[124:127], v[176:179], v[192:195], v[124:127]
	v_mfma_f32_16x16x32_bf16 v[120:123], v[184:187], v[192:195], v[120:123]
	v_mfma_f32_16x16x32_bf16 v[108:111], v[176:179], v[200:203], v[108:111]
	v_mfma_f32_16x16x32_bf16 v[104:107], v[184:187], v[200:203], v[104:107]
	v_mfma_f32_16x16x32_bf16 v[92:95], v[176:179], v[208:211], v[92:95]
	v_mfma_f32_16x16x32_bf16 v[88:91], v[184:187], v[208:211], v[88:91]
	v_mfma_f32_16x16x32_bf16 v[68:71], v[176:179], v[216:219], v[68:71]
	v_mfma_f32_16x16x32_bf16 v[64:67], v[184:187], v[216:219], v[64:67]
	v_mfma_f32_16x16x32_bf16 v[124:127], v[180:183], v[196:199], v[124:127]
	v_mfma_f32_16x16x32_bf16 v[120:123], v[188:191], v[196:199], v[120:123]
	v_mfma_f32_16x16x32_bf16 v[108:111], v[180:183], v[204:207], v[108:111]
	v_mfma_f32_16x16x32_bf16 v[104:107], v[188:191], v[204:207], v[104:107]
	v_mfma_f32_16x16x32_bf16 v[92:95], v[180:183], v[212:215], v[92:95]
	v_mfma_f32_16x16x32_bf16 v[88:91], v[188:191], v[212:215], v[88:91]
	v_mfma_f32_16x16x32_bf16 v[68:71], v[180:183], v[220:223], v[68:71]
	v_mfma_f32_16x16x32_bf16 v[64:67], v[188:191], v[220:223], v[64:67]
	s_barrier
	s_setprio 0
	s_add_i32 s48, s88, s97
	v_lshl_add_u64 v[152:153], v[152:153], 0, s[18:19]
	s_mov_b32 m0, s48
	ds_read_b128 v[192:195], v161 offset:49152
	ds_read_b128 v[196:199], v161 offset:50176
	ds_read_b128 v[200:203], v161 offset:51200
	ds_read_b128 v[204:207], v161 offset:52224
	ds_read_b128 v[208:211], v161 offset:53248
	ds_read_b128 v[212:215], v161 offset:54272
	ds_read_b128 v[216:219], v161 offset:55296
	ds_read_b128 v[220:223], v161 offset:56320
	global_load_lds_dwordx4 v[152:153], off sc0
	s_add_i32 m0, s48, 0x2000
	s_add_u32 s46, s46, 0x100080
	v_lshl_add_u64 v[152:153], v[224:225], 0, s[18:19]
	s_addc_u32 s47, s47, 0
	s_add_i32 s48, s89, s97
	global_load_lds_dwordx4 v[152:153], off sc0
	v_lshl_add_u64 v[152:153], s[46:47], 0, v[132:133]
	s_mov_b32 m0, s48
	s_nop 0
	global_load_lds_dwordx4 v[152:153], off sc0
	v_lshl_add_u64 v[152:153], s[46:47], 0, v[136:137]
	s_add_i32 m0, s48, 0x2000
	s_nop 0
	global_load_lds_dwordx4 v[152:153], off sc0
	v_lshl_add_u64 v[152:153], v[226:227], 0, s[18:19]
	s_mov_b32 m0, s68
	s_nop 0
	global_load_lds_dwordx4 v[152:153], off sc0
	v_lshl_add_u64 v[152:153], v[228:229], 0, s[18:19]
	s_mov_b32 m0, s69
	s_nop 0
	global_load_lds_dwordx4 v[152:153], off sc0
	s_waitcnt vmcnt(8)
	s_waitcnt lgkmcnt(0)
	s_setprio 1
	s_barrier
	v_mfma_f32_16x16x32_bf16 v[60:63], v[148:151], v[192:195], v[60:63]
	v_mfma_f32_16x16x32_bf16 v[56:59], v[168:171], v[192:195], v[56:59]
	v_mfma_f32_16x16x32_bf16 v[36:39], v[148:151], v[200:203], v[36:39]
	v_mfma_f32_16x16x32_bf16 v[32:35], v[168:171], v[200:203], v[32:35]
	v_mfma_f32_16x16x32_bf16 v[20:23], v[148:151], v[208:211], v[20:23]
	v_mfma_f32_16x16x32_bf16 v[16:19], v[168:171], v[208:211], v[16:19]
	v_mfma_f32_16x16x32_bf16 v[4:7], v[148:151], v[216:219], v[4:7]
	v_mfma_f32_16x16x32_bf16 v[0:3], v[168:171], v[216:219], v[0:3]
	v_mfma_f32_16x16x32_bf16 v[60:63], v[164:167], v[196:199], v[60:63]
	v_mfma_f32_16x16x32_bf16 v[56:59], v[172:175], v[196:199], v[56:59]
	v_mfma_f32_16x16x32_bf16 v[36:39], v[164:167], v[204:207], v[36:39]
	v_mfma_f32_16x16x32_bf16 v[32:35], v[172:175], v[204:207], v[32:35]
	v_mfma_f32_16x16x32_bf16 v[20:23], v[164:167], v[212:215], v[20:23]
	v_mfma_f32_16x16x32_bf16 v[16:19], v[172:175], v[212:215], v[16:19]
	v_mfma_f32_16x16x32_bf16 v[4:7], v[164:167], v[220:223], v[4:7]
	v_mfma_f32_16x16x32_bf16 v[0:3], v[172:175], v[220:223], v[0:3]
	s_setprio 0
	s_setprio 1
	v_mfma_f32_16x16x32_bf16 v[76:79], v[176:179], v[192:195], v[76:79]
	v_mfma_f32_16x16x32_bf16 v[72:75], v[184:187], v[192:195], v[72:75]
	v_mfma_f32_16x16x32_bf16 v[44:47], v[176:179], v[200:203], v[44:47]
	v_mfma_f32_16x16x32_bf16 v[40:43], v[184:187], v[200:203], v[40:43]
	v_mfma_f32_16x16x32_bf16 v[28:31], v[176:179], v[208:211], v[28:31]
	v_mfma_f32_16x16x32_bf16 v[24:27], v[184:187], v[208:211], v[24:27]
	v_mfma_f32_16x16x32_bf16 v[12:15], v[176:179], v[216:219], v[12:15]
	v_mfma_f32_16x16x32_bf16 v[8:11], v[184:187], v[216:219], v[8:11]
	v_mfma_f32_16x16x32_bf16 v[76:79], v[180:183], v[196:199], v[76:79]
	v_mfma_f32_16x16x32_bf16 v[72:75], v[188:191], v[196:199], v[72:75]
	v_mfma_f32_16x16x32_bf16 v[44:47], v[180:183], v[204:207], v[44:47]
	v_mfma_f32_16x16x32_bf16 v[40:43], v[188:191], v[204:207], v[40:43]
	v_mfma_f32_16x16x32_bf16 v[28:31], v[180:183], v[212:215], v[28:31]
	v_mfma_f32_16x16x32_bf16 v[24:27], v[188:191], v[212:215], v[24:27]
	v_mfma_f32_16x16x32_bf16 v[12:15], v[180:183], v[220:223], v[12:15]
	v_mfma_f32_16x16x32_bf16 v[8:11], v[188:191], v[220:223], v[8:11]
	s_barrier
	s_setprio 0
	s_add_u32 s85, s85, 0x100
	s_addc_u32 s86, s86, 0
	s_add_u32 s44, s44, 0x100
	s_addc_u32 s45, s45, 0
	s_cmp_ge_u32 s87, s84
	s_mov_b32 s46, s87
	s_cbranch_scc0 .LBB0_2289
	v_readlane_b32 s44, v254, 27
	v_readlane_b32 s45, v254, 28
	s_and_b64 vcc, exec, s[44:45]
	s_cbranch_vccz .LBB0_2297
	s_barrier
	s_cmp_lt_i32 s16, 0
	s_mov_b64 s[44:45], -1
	s_cbranch_scc1 .LBB0_2298

.LBB0_2453:
	ds_read_b128 v[128:131], v228
	ds_read_b128 v[132:135], v228 offset:1024
	ds_read_b128 v[136:139], v228 offset:2048
	ds_read_b128 v[140:143], v228 offset:3072
	ds_read_b128 v[144:147], v229
	ds_read_b128 v[148:151], v229 offset:1024
	ds_read_b128 v[152:155], v229 offset:2048
	ds_read_b128 v[156:159], v229 offset:3072
	s_add_i32 s79, s46, 2
	s_add_u32 s47, s44, 0xffc00080
	s_addc_u32 s48, s45, -1
	s_cmp_eq_u32 s75, s46
	s_cselect_b32 s46, s43, s77
	s_cselect_b32 s49, s35, s48
	s_cselect_b32 s48, s41, s47
	s_cselect_b32 s47, s31, s78
	v_lshl_add_u64 v[208:209], s[44:45], 0, v[202:203]
	s_add_i32 m0, s94, 0xc000
	ds_read_b128 v[160:163], v230
	ds_read_b128 v[164:167], v230 offset:1024
	ds_read_b128 v[168:171], v230 offset:2048
	ds_read_b128 v[172:175], v230 offset:3072
	ds_read_b128 v[176:179], v230 offset:4096
	ds_read_b128 v[180:183], v230 offset:5120
	ds_read_b128 v[184:187], v230 offset:6144
	ds_read_b128 v[188:191], v230 offset:7168
	global_load_lds_dwordx4 v[208:209], off sc0
	v_lshl_add_u64 v[208:209], s[44:45], 0, v[204:205]
	s_add_i32 m0, s94, 0xe000
	s_nop 0
	global_load_lds_dwordx4 v[208:209], off sc0
	s_waitcnt vmcnt(8)
	s_waitcnt lgkmcnt(0)
	s_setprio 1
	s_barrier
	v_mfma_f32_16x16x32_bf16 v[112:115], v[128:131], v[160:163], v[112:115]
	v_mfma_f32_16x16x32_bf16 v[116:119], v[136:139], v[160:163], v[116:119]
	v_mfma_f32_16x16x32_bf16 v[100:103], v[128:131], v[168:171], v[100:103]
	v_mfma_f32_16x16x32_bf16 v[96:99], v[136:139], v[168:171], v[96:99]
	v_mfma_f32_16x16x32_bf16 v[84:87], v[128:131], v[176:179], v[84:87]
	v_mfma_f32_16x16x32_bf16 v[80:83], v[136:139], v[176:179], v[80:83]
	v_mfma_f32_16x16x32_bf16 v[52:55], v[128:131], v[184:187], v[52:55]
	v_mfma_f32_16x16x32_bf16 v[48:51], v[136:139], v[184:187], v[48:51]
	v_mfma_f32_16x16x32_bf16 v[112:115], v[132:135], v[164:167], v[112:115]
	v_mfma_f32_16x16x32_bf16 v[116:119], v[140:143], v[164:167], v[116:119]
	v_mfma_f32_16x16x32_bf16 v[100:103], v[132:135], v[172:175], v[100:103]
	v_mfma_f32_16x16x32_bf16 v[96:99], v[140:143], v[172:175], v[96:99]
	v_mfma_f32_16x16x32_bf16 v[84:87], v[132:135], v[180:183], v[84:87]
	v_mfma_f32_16x16x32_bf16 v[80:83], v[140:143], v[180:183], v[80:83]
	v_mfma_f32_16x16x32_bf16 v[52:55], v[132:135], v[188:191], v[52:55]
	v_mfma_f32_16x16x32_bf16 v[48:51], v[140:143], v[188:191], v[48:51]
	s_setprio 0
	s_setprio 1
	v_mfma_f32_16x16x32_bf16 v[124:127], v[144:147], v[160:163], v[124:127]
	v_mfma_f32_16x16x32_bf16 v[120:123], v[152:155], v[160:163], v[120:123]
	v_mfma_f32_16x16x32_bf16 v[108:111], v[144:147], v[168:171], v[108:111]
	v_mfma_f32_16x16x32_bf16 v[104:107], v[152:155], v[168:171], v[104:107]
	v_mfma_f32_16x16x32_bf16 v[92:95], v[144:147], v[176:179], v[92:95]
	v_mfma_f32_16x16x32_bf16 v[88:91], v[152:155], v[176:179], v[88:91]
	v_mfma_f32_16x16x32_bf16 v[68:71], v[144:147], v[184:187], v[68:71]
	v_mfma_f32_16x16x32_bf16 v[64:67], v[152:155], v[184:187], v[64:67]
	v_mfma_f32_16x16x32_bf16 v[124:127], v[148:151], v[164:167], v[124:127]
	v_mfma_f32_16x16x32_bf16 v[120:123], v[156:159], v[164:167], v[120:123]
	v_mfma_f32_16x16x32_bf16 v[108:111], v[148:151], v[172:175], v[108:111]
	v_mfma_f32_16x16x32_bf16 v[104:107], v[156:159], v[172:175], v[104:107]
	v_mfma_f32_16x16x32_bf16 v[92:95], v[148:151], v[180:183], v[92:95]
	v_mfma_f32_16x16x32_bf16 v[88:91], v[156:159], v[180:183], v[88:91]
	v_mfma_f32_16x16x32_bf16 v[68:71], v[148:151], v[188:191], v[68:71]
	v_mfma_f32_16x16x32_bf16 v[64:67], v[156:159], v[188:191], v[64:67]
	s_barrier
	s_setprio 0
	s_add_i32 s80, s68, s97
	v_lshl_add_u64 v[208:209], s[46:47], 0, v[194:195]
	s_mov_b32 m0, s80
	ds_read_b128 v[160:163], v230 offset:16384
	ds_read_b128 v[164:167], v230 offset:17408
	ds_read_b128 v[168:171], v230 offset:18432
	ds_read_b128 v[172:175], v230 offset:19456
	ds_read_b128 v[176:179], v230 offset:20480
	ds_read_b128 v[180:183], v230 offset:21504
	ds_read_b128 v[184:187], v230 offset:22528
	ds_read_b128 v[188:191], v230 offset:23552
	global_load_lds_dwordx4 v[208:209], off sc0
	s_add_i32 m0, s80, 0x2000
	s_add_u32 s80, s46, 0x400000
	v_lshl_add_u64 v[210:211], s[46:47], 0, v[198:199]
	s_addc_u32 s81, s47, 0
	s_add_i32 s84, s69, s97
	global_load_lds_dwordx4 v[210:211], off sc0
	v_lshl_add_u64 v[212:213], s[80:81], 0, v[194:195]
	s_mov_b32 m0, s84
	v_lshl_add_u64 v[214:215], s[48:49], 0, v[196:197]
	global_load_lds_dwordx4 v[212:213], off sc0
	v_lshl_add_u64 v[212:213], s[80:81], 0, v[198:199]
	s_add_i32 m0, s84, 0x2000
	s_nop 0
	global_load_lds_dwordx4 v[212:213], off sc0
	v_lshl_add_u64 v[212:213], s[48:49], 0, v[192:193]
	s_mov_b32 m0, s94
	s_nop 0
	global_load_lds_dwordx4 v[212:213], off sc0
	s_mov_b32 m0, s51
	s_nop 0
	global_load_lds_dwordx4 v[214:215], off sc0
	s_waitcnt vmcnt(8)
	s_waitcnt lgkmcnt(0)
	s_setprio 1
	s_barrier
	v_mfma_f32_16x16x32_bf16 v[60:63], v[128:131], v[160:163], v[60:63]
	v_mfma_f32_16x16x32_bf16 v[56:59], v[136:139], v[160:163], v[56:59]
	v_mfma_f32_16x16x32_bf16 v[36:39], v[128:131], v[168:171], v[36:39]
	v_mfma_f32_16x16x32_bf16 v[32:35], v[136:139], v[168:171], v[32:35]
	v_mfma_f32_16x16x32_bf16 v[20:23], v[128:131], v[176:179], v[20:23]
	v_mfma_f32_16x16x32_bf16 v[16:19], v[136:139], v[176:179], v[16:19]
	v_mfma_f32_16x16x32_bf16 v[4:7], v[128:131], v[184:187], v[4:7]
	v_mfma_f32_16x16x32_bf16 v[0:3], v[136:139], v[184:187], v[0:3]
	v_mfma_f32_16x16x32_bf16 v[60:63], v[132:135], v[164:167], v[60:63]
	v_mfma_f32_16x16x32_bf16 v[56:59], v[140:143], v[164:167], v[56:59]
	v_mfma_f32_16x16x32_bf16 v[36:39], v[132:135], v[172:175], v[36:39]
	v_mfma_f32_16x16x32_bf16 v[32:35], v[140:143], v[172:175], v[32:35]
	v_mfma_f32_16x16x32_bf16 v[20:23], v[132:135], v[180:183], v[20:23]
	v_mfma_f32_16x16x32_bf16 v[16:19], v[140:143], v[180:183], v[16:19]
	v_mfma_f32_16x16x32_bf16 v[4:7], v[132:135], v[188:191], v[4:7]
	v_mfma_f32_16x16x32_bf16 v[0:3], v[140:143], v[188:191], v[0:3]
	s_setprio 0
	s_setprio 1
	v_mfma_f32_16x16x32_bf16 v[76:79], v[144:147], v[160:163], v[76:79]
	v_mfma_f32_16x16x32_bf16 v[72:75], v[152:155], v[160:163], v[72:75]
	v_mfma_f32_16x16x32_bf16 v[44:47], v[144:147], v[168:171], v[44:47]
	v_mfma_f32_16x16x32_bf16 v[40:43], v[152:155], v[168:171], v[40:43]
	v_mfma_f32_16x16x32_bf16 v[28:31], v[144:147], v[176:179], v[28:31]
	v_mfma_f32_16x16x32_bf16 v[24:27], v[152:155], v[176:179], v[24:27]
	v_mfma_f32_16x16x32_bf16 v[12:15], v[144:147], v[184:187], v[12:15]
	v_mfma_f32_16x16x32_bf16 v[8:11], v[152:155], v[184:187], v[8:11]
	v_mfma_f32_16x16x32_bf16 v[76:79], v[148:151], v[164:167], v[76:79]
	v_mfma_f32_16x16x32_bf16 v[72:75], v[156:159], v[164:167], v[72:75]
	v_mfma_f32_16x16x32_bf16 v[44:47], v[148:151], v[172:175], v[44:47]
	v_mfma_f32_16x16x32_bf16 v[40:43], v[156:159], v[172:175], v[40:43]
	v_mfma_f32_16x16x32_bf16 v[28:31], v[148:151], v[180:183], v[28:31]
	v_mfma_f32_16x16x32_bf16 v[24:27], v[156:159], v[180:183], v[24:27]
	v_mfma_f32_16x16x32_bf16 v[12:15], v[148:151], v[188:191], v[12:15]
	v_mfma_f32_16x16x32_bf16 v[8:11], v[156:159], v[188:191], v[8:11]
	s_barrier
	s_setprio 0
	s_add_i32 s80, 0, 0x18000
	s_add_i32 s81, 0, 0x1c000
	v_add_u32_e32 v140, s80, v226
	v_add_u32_e32 v156, s81, v226
	ds_read_b128 v[128:131], v140
	ds_read_b128 v[132:135], v140 offset:1024
	ds_read_b128 v[136:139], v140 offset:2048
	ds_read_b128 v[140:143], v140 offset:3072
	ds_read_b128 v[144:147], v156
	ds_read_b128 v[148:151], v156 offset:1024
	ds_read_b128 v[152:155], v156 offset:2048
	ds_read_b128 v[156:159], v156 offset:3072
	s_add_u32 s48, s48, 0x400000
	s_addc_u32 s49, s49, 0
	s_mov_b32 m0, s52
	v_lshl_add_u64 v[216:217], s[48:49], 0, v[192:193]
	ds_read_b128 v[160:163], v230 offset:32768
	ds_read_b128 v[164:167], v230 offset:33792
	ds_read_b128 v[168:171], v230 offset:34816
	ds_read_b128 v[172:175], v230 offset:35840
	ds_read_b128 v[176:179], v230 offset:36864
	ds_read_b128 v[180:183], v230 offset:37888
	ds_read_b128 v[184:187], v230 offset:38912
	ds_read_b128 v[188:191], v230 offset:39936
	global_load_lds_dwordx4 v[216:217], off sc0
	v_lshl_add_u64 v[216:217], s[48:49], 0, v[196:197]
	s_mov_b32 m0, s53
	s_nop 0
	global_load_lds_dwordx4 v[216:217], off sc0
	s_waitcnt vmcnt(8)
	s_waitcnt lgkmcnt(0)
	s_setprio 1
	s_barrier
	v_mfma_f32_16x16x32_bf16 v[112:115], v[128:131], v[160:163], v[112:115]
	v_mfma_f32_16x16x32_bf16 v[116:119], v[136:139], v[160:163], v[116:119]
	v_mfma_f32_16x16x32_bf16 v[100:103], v[128:131], v[168:171], v[100:103]
	v_mfma_f32_16x16x32_bf16 v[96:99], v[136:139], v[168:171], v[96:99]
	v_mfma_f32_16x16x32_bf16 v[84:87], v[128:131], v[176:179], v[84:87]
	v_mfma_f32_16x16x32_bf16 v[80:83], v[136:139], v[176:179], v[80:83]
	v_mfma_f32_16x16x32_bf16 v[52:55], v[128:131], v[184:187], v[52:55]
	v_mfma_f32_16x16x32_bf16 v[48:51], v[136:139], v[184:187], v[48:51]
	v_mfma_f32_16x16x32_bf16 v[112:115], v[132:135], v[164:167], v[112:115]
	v_mfma_f32_16x16x32_bf16 v[116:119], v[140:143], v[164:167], v[116:119]
	v_mfma_f32_16x16x32_bf16 v[100:103], v[132:135], v[172:175], v[100:103]
	v_mfma_f32_16x16x32_bf16 v[96:99], v[140:143], v[172:175], v[96:99]
	v_mfma_f32_16x16x32_bf16 v[84:87], v[132:135], v[180:183], v[84:87]
	v_mfma_f32_16x16x32_bf16 v[80:83], v[140:143], v[180:183], v[80:83]
	v_mfma_f32_16x16x32_bf16 v[52:55], v[132:135], v[188:191], v[52:55]
	v_mfma_f32_16x16x32_bf16 v[48:51], v[140:143], v[188:191], v[48:51]
	s_setprio 0
	s_setprio 1
	v_mfma_f32_16x16x32_bf16 v[124:127], v[144:147], v[160:163], v[124:127]
	v_mfma_f32_16x16x32_bf16 v[120:123], v[152:155], v[160:163], v[120:123]
	v_mfma_f32_16x16x32_bf16 v[108:111], v[144:147], v[168:171], v[108:111]
	v_mfma_f32_16x16x32_bf16 v[104:107], v[152:155], v[168:171], v[104:107]
	v_mfma_f32_16x16x32_bf16 v[92:95], v[144:147], v[176:179], v[92:95]
	v_mfma_f32_16x16x32_bf16 v[88:91], v[152:155], v[176:179], v[88:91]
	v_mfma_f32_16x16x32_bf16 v[68:71], v[144:147], v[184:187], v[68:71]
	v_mfma_f32_16x16x32_bf16 v[64:67], v[152:155], v[184:187], v[64:67]
	v_mfma_f32_16x16x32_bf16 v[124:127], v[148:151], v[164:167], v[124:127]
	v_mfma_f32_16x16x32_bf16 v[120:123], v[156:159], v[164:167], v[120:123]
	v_mfma_f32_16x16x32_bf16 v[108:111], v[148:151], v[172:175], v[108:111]
	v_mfma_f32_16x16x32_bf16 v[104:107], v[156:159], v[172:175], v[104:107]
	v_mfma_f32_16x16x32_bf16 v[92:95], v[148:151], v[180:183], v[92:95]
	v_mfma_f32_16x16x32_bf16 v[88:91], v[156:159], v[180:183], v[88:91]
	v_mfma_f32_16x16x32_bf16 v[68:71], v[148:151], v[188:191], v[68:71]
	v_mfma_f32_16x16x32_bf16 v[64:67], v[156:159], v[188:191], v[64:67]
	s_barrier
	s_setprio 0
	s_add_i32 s48, s80, s97
	v_lshl_add_u64 v[208:209], v[208:209], 0, s[12:13]
	s_mov_b32 m0, s48
	ds_read_b128 v[160:163], v230 offset:49152
	ds_read_b128 v[164:167], v230 offset:50176
	ds_read_b128 v[168:171], v230 offset:51200
	ds_read_b128 v[172:175], v230 offset:52224
	ds_read_b128 v[176:179], v230 offset:53248
	ds_read_b128 v[180:183], v230 offset:54272
	ds_read_b128 v[184:187], v230 offset:55296
	ds_read_b128 v[188:191], v230 offset:56320
	global_load_lds_dwordx4 v[208:209], off sc0
	s_add_i32 m0, s48, 0x2000
	s_add_u32 s46, s46, 0x400080
	v_lshl_add_u64 v[208:209], v[210:211], 0, s[12:13]
	s_addc_u32 s47, s47, 0
	s_add_i32 s48, s81, s97
	global_load_lds_dwordx4 v[208:209], off sc0
	v_lshl_add_u64 v[208:209], s[46:47], 0, v[194:195]
	s_mov_b32 m0, s48
	s_nop 0
	global_load_lds_dwordx4 v[208:209], off sc0
	v_lshl_add_u64 v[208:209], s[46:47], 0, v[198:199]
	s_add_i32 m0, s48, 0x2000
	s_nop 0
	global_load_lds_dwordx4 v[208:209], off sc0
	v_lshl_add_u64 v[208:209], v[212:213], 0, s[12:13]
	s_mov_b32 m0, s54
	s_nop 0
	global_load_lds_dwordx4 v[208:209], off sc0
	v_lshl_add_u64 v[208:209], v[214:215], 0, s[12:13]
	s_mov_b32 m0, s55
	s_nop 0
	global_load_lds_dwordx4 v[208:209], off sc0
	s_waitcnt vmcnt(8)
	s_waitcnt lgkmcnt(0)
	s_setprio 1
	s_barrier
	v_mfma_f32_16x16x32_bf16 v[60:63], v[128:131], v[160:163], v[60:63]
	v_mfma_f32_16x16x32_bf16 v[56:59], v[136:139], v[160:163], v[56:59]
	v_mfma_f32_16x16x32_bf16 v[36:39], v[128:131], v[168:171], v[36:39]
	v_mfma_f32_16x16x32_bf16 v[32:35], v[136:139], v[168:171], v[32:35]
	v_mfma_f32_16x16x32_bf16 v[20:23], v[128:131], v[176:179], v[20:23]
	v_mfma_f32_16x16x32_bf16 v[16:19], v[136:139], v[176:179], v[16:19]
	v_mfma_f32_16x16x32_bf16 v[4:7], v[128:131], v[184:187], v[4:7]
	v_mfma_f32_16x16x32_bf16 v[0:3], v[136:139], v[184:187], v[0:3]
	v_mfma_f32_16x16x32_bf16 v[60:63], v[132:135], v[164:167], v[60:63]
	v_mfma_f32_16x16x32_bf16 v[56:59], v[140:143], v[164:167], v[56:59]
	v_mfma_f32_16x16x32_bf16 v[36:39], v[132:135], v[172:175], v[36:39]
	v_mfma_f32_16x16x32_bf16 v[32:35], v[140:143], v[172:175], v[32:35]
	v_mfma_f32_16x16x32_bf16 v[20:23], v[132:135], v[180:183], v[20:23]
	v_mfma_f32_16x16x32_bf16 v[16:19], v[140:143], v[180:183], v[16:19]
	v_mfma_f32_16x16x32_bf16 v[4:7], v[132:135], v[188:191], v[4:7]
	v_mfma_f32_16x16x32_bf16 v[0:3], v[140:143], v[188:191], v[0:3]
	s_setprio 0
	s_setprio 1
	v_mfma_f32_16x16x32_bf16 v[76:79], v[144:147], v[160:163], v[76:79]
	v_mfma_f32_16x16x32_bf16 v[72:75], v[152:155], v[160:163], v[72:75]
	v_mfma_f32_16x16x32_bf16 v[44:47], v[144:147], v[168:171], v[44:47]
	v_mfma_f32_16x16x32_bf16 v[40:43], v[152:155], v[168:171], v[40:43]
	v_mfma_f32_16x16x32_bf16 v[28:31], v[144:147], v[176:179], v[28:31]
	v_mfma_f32_16x16x32_bf16 v[24:27], v[152:155], v[176:179], v[24:27]
	v_mfma_f32_16x16x32_bf16 v[12:15], v[144:147], v[184:187], v[12:15]
	v_mfma_f32_16x16x32_bf16 v[8:11], v[152:155], v[184:187], v[8:11]
	v_mfma_f32_16x16x32_bf16 v[76:79], v[148:151], v[164:167], v[76:79]
	v_mfma_f32_16x16x32_bf16 v[72:75], v[156:159], v[164:167], v[72:75]
	v_mfma_f32_16x16x32_bf16 v[44:47], v[148:151], v[172:175], v[44:47]
	v_mfma_f32_16x16x32_bf16 v[40:43], v[156:159], v[172:175], v[40:43]
	v_mfma_f32_16x16x32_bf16 v[28:31], v[148:151], v[180:183], v[28:31]
	v_mfma_f32_16x16x32_bf16 v[24:27], v[156:159], v[180:183], v[24:27]
	v_mfma_f32_16x16x32_bf16 v[12:15], v[148:151], v[188:191], v[12:15]
	v_mfma_f32_16x16x32_bf16 v[8:11], v[156:159], v[188:191], v[8:11]
	s_barrier
	s_setprio 0
	s_add_u32 s77, s77, 0x100
	s_addc_u32 s78, s78, 0
	s_add_u32 s44, s44, 0x100
	s_addc_u32 s45, s45, 0
	s_cmp_ge_u32 s79, s76
	s_mov_b32 s46, s79
	s_cbranch_scc0 .LBB0_2453
	v_readlane_b32 s44, v254, 27
	v_readlane_b32 s45, v254, 28
	s_and_b64 vcc, exec, s[44:45]
	s_cbranch_vccz .LBB0_2461
	s_barrier
	s_cmp_lt_i32 s10, 0
	s_mov_b64 s[44:45], -1
	s_cbranch_scc1 .LBB0_2462
